# conv-gate epilogue: removed 256 dead zero-inits in front of full-row rotate DPP moves
# speedup vs baseline: 1.1270x; 1.0084x over previous
.LBB0_113:
	s_or_b64 exec, exec, s[0:1]
	v_ffbh_u32_e32 v0, v135
	v_min_u32_e32 v0, 32, v0
	v_lshlrev_b64 v[114:115], v0, v[134:135]
	v_min_u32_e32 v114, 1, v114
	v_or_b32_e32 v114, v115, v114
	v_cvt_f32_u32_e32 v114, v114
	v_sub_u32_e32 v0, 32, v0
	s_lshl_b32 s5, s78, 7
	v_add_u32_e32 v180, s5, v130
	v_ldexp_f32 v0, v114, v0
	v_mul_f32_e32 v0, 0x33800000, v0
	v_fmamk_f32 v0, v0, 0x3a800000, v210
	s_nop 0
	v_rsq_f32_e32 v0, v0
	s_nop 0
	s_nop 0
	v_mov_b32_e32 v178, v0
	v_ffbh_u32_e32 v0, v133
	v_min_u32_e32 v0, 32, v0
	v_pk_mul_f32 v[186:187], v[110:111], v[178:179] op_sel_hi:[1,0]
	v_lshlrev_b64 v[110:111], v0, v[132:133]
	v_min_u32_e32 v110, 1, v110
	v_or_b32_e32 v110, v111, v110
	v_cvt_f32_u32_e32 v110, v110
	v_sub_u32_e32 v0, 32, v0
	v_pk_mul_f32 v[184:185], v[112:113], v[178:179] op_sel_hi:[1,0]
	v_ldexp_f32 v0, v110, v0
	v_mul_f32_e32 v0, 0x33800000, v0
	v_fmamk_f32 v0, v0, 0x3a800000, v210
	s_nop 0
	v_rsq_f32_e32 v0, v0
	s_nop 0
	s_nop 0
	v_mov_b32_e32 v182, v0
	v_pk_mul_f32 v[188:189], v[108:109], v[182:183] op_sel_hi:[1,0]
	v_pk_mul_f32 v[198:199], v[106:107], v[182:183] op_sel_hi:[1,0]
	v_ashrrev_i32_e32 v181, 31, v180
	v_lshlrev_b64 v[118:119], 2, v[180:181]
	v_lshl_add_u64 v[106:107], s[44:45], 0, v[118:119]
	v_lshl_add_u64 v[108:109], s[60:61], 0, v[118:119]
	global_load_dwordx4 v[122:125], v[106:107], off
	global_load_dwordx4 v[126:129], v[108:109], off
	v_lshl_add_u64 v[106:107], s[2:3], 0, v[118:119]
	global_load_dwordx4 v[130:133], v[106:107], off
	v_lshl_add_u64 v[106:107], s[48:49], 0, v[118:119]
	global_load_dwordx4 v[134:137], v[106:107], off
	s_nop 1
	v_cmp_lt_u32_e32 vcc, 1, v183
	v_mov_b32_dpp v206, v170 row_ror:1 row_mask:0xf bank_mask:0xf
	v_mov_b32_dpp v204, v170 row_ror:2 row_mask:0xf bank_mask:0xf
	v_mov_b32_dpp v207, v171 row_ror:1 row_mask:0xf bank_mask:0xf
	v_mov_b32_dpp v205, v171 row_ror:2 row_mask:0xf bank_mask:0xf
	v_mov_b32_dpp v202, v172 row_ror:1 row_mask:0xf bank_mask:0xf
	v_mov_b32_dpp v200, v172 row_ror:2 row_mask:0xf bank_mask:0xf
	v_mov_b32_dpp v203, v173 row_ror:1 row_mask:0xf bank_mask:0xf
	v_mov_b32_dpp v201, v173 row_ror:2 row_mask:0xf bank_mask:0xf
	v_mov_b32_dpp v241, v186 row_ror:1 row_mask:0xf bank_mask:0xf
	v_mov_b32_dpp v240, v186 row_ror:2 row_mask:0xf bank_mask:0xf
	v_mov_b32_dpp v245, v187 row_ror:1 row_mask:0xf bank_mask:0xf
	v_mov_b32_dpp v244, v187 row_ror:2 row_mask:0xf bank_mask:0xf
	v_mov_b32_dpp v229, v184 row_ror:1 row_mask:0xf bank_mask:0xf
	v_mov_b32_dpp v228, v184 row_ror:2 row_mask:0xf bank_mask:0xf
	v_mov_b32_dpp v235, v185 row_ror:1 row_mask:0xf bank_mask:0xf
	v_mov_b32_dpp v233, v185 row_ror:2 row_mask:0xf bank_mask:0xf
	v_mov_b32_dpp v234, v198 row_ror:1 row_mask:0xf bank_mask:0xf
	v_mov_b32_dpp v231, v198 row_ror:2 row_mask:0xf bank_mask:0xf
	v_mov_b32_dpp v239, v199 row_ror:1 row_mask:0xf bank_mask:0xf
	v_mov_b32_dpp v237, v199 row_ror:2 row_mask:0xf bank_mask:0xf
	v_mov_b32_dpp v151, v188 row_ror:1 row_mask:0xf bank_mask:0xf
	v_mov_b32_dpp v0, v188 row_ror:2 row_mask:0xf bank_mask:0xf
	v_mov_b32_dpp v227, v189 row_ror:1 row_mask:0xf bank_mask:0xf
	v_mov_b32_dpp v213, v189 row_ror:2 row_mask:0xf bank_mask:0xf
	v_mov_b32_dpp v243, v176 row_ror:1 row_mask:0xf bank_mask:0xf
	v_mov_b32_dpp v242, v176 row_ror:2 row_mask:0xf bank_mask:0xf
	v_mov_b32_dpp v247, v177 row_ror:1 row_mask:0xf bank_mask:0xf
	v_mov_b32_dpp v246, v177 row_ror:2 row_mask:0xf bank_mask:0xf
	v_mov_b32_dpp v232, v174 row_ror:1 row_mask:0xf bank_mask:0xf
	v_mov_b32_dpp v230, v174 row_ror:2 row_mask:0xf bank_mask:0xf
	v_mov_b32_dpp v238, v175 row_ror:1 row_mask:0xf bank_mask:0xf
	v_mov_b32_dpp v236, v175 row_ror:2 row_mask:0xf bank_mask:0xf
	v_lshl_add_u64 v[106:107], s[96:97], 0, v[118:119]
	v_lshl_add_u64 v[108:109], s[62:63], 0, v[118:119]
	global_load_dwordx4 v[114:117], v[106:107], off
	global_load_dwordx4 v[110:113], v[108:109], off
	v_lshl_add_u64 v[106:107], s[64:65], 0, v[118:119]
	v_lshl_add_u64 v[118:119], s[66:67], 0, v[118:119]
	global_load_dwordx4 v[106:109], v[106:107], off
	s_nop 1
	global_load_dwordx4 v[118:121], v[118:119], off
	s_nop 1
	v_mov_b32_dpp v190, v158 row_ror:1 row_mask:0xf bank_mask:0xf
	v_mov_b32_dpp v194, v158 row_ror:2 row_mask:0xf bank_mask:0xf
	v_mov_b32_dpp v191, v159 row_ror:1 row_mask:0xf bank_mask:0xf
	v_mov_b32_dpp v195, v159 row_ror:2 row_mask:0xf bank_mask:0xf
	v_mov_b32_dpp v192, v156 row_ror:1 row_mask:0xf bank_mask:0xf
	v_mov_b32_dpp v196, v156 row_ror:2 row_mask:0xf bank_mask:0xf
	v_mov_b32_dpp v193, v157 row_ror:1 row_mask:0xf bank_mask:0xf
	v_mov_b32_dpp v197, v157 row_ror:2 row_mask:0xf bank_mask:0xf
	s_and_saveexec_b64 s[0:1], vcc
	s_mov_b32 s50, 0x20000
	s_mov_b32 s47, 0xbfb8aa3b
	s_cbranch_execz .Lcg_skip0
	s_waitcnt vmcnt(4)
	v_pk_fma_f32 v[248:249], v[124:125], v[200:201], v[136:137]
	s_nop 0
	v_pk_fma_f32 v[248:249], v[128:129], v[202:203], v[248:249]
	s_nop 0
	v_pk_fma_f32 v[172:173], v[172:173], v[132:133], v[248:249]
	v_pk_fma_f32 v[248:249], v[122:123], v[204:205], v[134:135]
	v_mul_f32_e32 v179, 0xbfb8aa3b, v173
	v_exp_f32_e32 v179, v179
	v_pk_fma_f32 v[248:249], v[126:127], v[206:207], v[248:249]
	v_mul_f32_e32 v250, 0xbfb8aa3b, v172
	v_pk_fma_f32 v[170:171], v[170:171], v[130:131], v[248:249]
	v_add_f32_e32 v179, 1.0, v179
	v_rcp_f32_e32 v251, v179
	v_mul_f32_e32 v179, 0xbfb8aa3b, v171
	v_exp_f32_e32 v179, v179
	v_mul_f32_e32 v248, 0xbfb8aa3b, v170
	v_exp_f32_e32 v250, v250
	v_exp_f32_e32 v248, v248
	v_add_f32_e32 v179, 1.0, v179
	v_rcp_f32_e32 v249, v179
	v_add_f32_e32 v250, 1.0, v250
	v_add_f32_e32 v179, 1.0, v248
	v_rcp_f32_e32 v248, v179
	v_rcp_f32_e32 v250, v250
	v_pk_mul_f32 v[170:171], v[170:171], v[248:249]
	v_pk_mul_f32 v[172:173], v[172:173], v[250:251]
	s_waitcnt vmcnt(0)
	v_pk_fma_f32 v[248:249], v[116:117], v[196:197], v[120:121]
	v_pk_fma_f32 v[250:251], v[114:115], v[194:195], v[118:119]
	v_pk_fma_f32 v[248:249], v[112:113], v[192:193], v[248:249]
	v_pk_fma_f32 v[250:251], v[110:111], v[190:191], v[250:251]
	v_pk_fma_f32 v[156:157], v[156:157], v[108:109], v[248:249]
	v_pk_fma_f32 v[158:159], v[158:159], v[106:107], v[250:251]
	v_pk_mul_f32 v[156:157], v[172:173], v[156:157]
	v_pk_mul_f32 v[158:159], v[170:171], v[158:159]
	s_nop 0
	v_cvt_pk_bf16_f32 v158, v158, v159
	v_cvt_pk_bf16_f32 v159, v156, v157
	v_mov_b64_e32 v[156:157], s[36:37]
	v_mad_i64_i32 v[156:157], s[28:29], v150, s46, v[156:157]
	v_lshl_add_u64 v[156:157], v[180:181], 1, v[156:157]
	global_store_dwordx2 v[156:157], v[158:159], off
.LBB0_115:
	s_or_b64 exec, exec, s[0:1]
	v_cmp_eq_u32_e64 s[42:43], 0, v183
	v_cndmask_b32_e32 v159, v205, v244, vcc
	v_cndmask_b32_e32 v158, v204, v240, vcc
	v_cndmask_b32_e64 v157, v245, v207, s[42:43]
	v_cndmask_b32_e64 v156, v241, v206, s[42:43]
	s_waitcnt vmcnt(4)
	v_pk_fma_f32 v[158:159], v[122:123], v[158:159], v[134:135]
	v_cndmask_b32_e32 v173, v201, v233, vcc
	v_cndmask_b32_e32 v172, v200, v228, vcc
	v_pk_fma_f32 v[156:157], v[126:127], v[156:157], v[158:159]
	v_cndmask_b32_e64 v171, v235, v203, s[42:43]
	v_cndmask_b32_e64 v170, v229, v202, s[42:43]
	v_pk_fma_f32 v[172:173], v[124:125], v[172:173], v[136:137]
	v_pk_fma_f32 v[156:157], v[186:187], v[130:131], v[156:157]
	v_pk_fma_f32 v[170:171], v[128:129], v[170:171], v[172:173]
	v_cndmask_b32_e32 v187, v244, v237, vcc
	v_cndmask_b32_e32 v186, v240, v231, vcc
	v_pk_fma_f32 v[170:171], v[184:185], v[132:133], v[170:171]
	v_cndmask_b32_e64 v185, v239, v245, s[42:43]
	v_cndmask_b32_e64 v184, v234, v241, s[42:43]
	v_pk_fma_f32 v[186:187], v[122:123], v[186:187], v[134:135]
	v_cndmask_b32_e32 v201, v233, v213, vcc
	v_pk_fma_f32 v[184:185], v[126:127], v[184:185], v[186:187]
	v_cndmask_b32_e32 v200, v228, v0, vcc
	v_pk_fma_f32 v[184:185], v[198:199], v[130:131], v[184:185]
	v_cndmask_b32_e64 v199, v227, v235, s[42:43]
	v_cndmask_b32_e64 v198, v151, v229, s[42:43]
	v_pk_fma_f32 v[200:201], v[124:125], v[200:201], v[136:137]
	v_cndmask_b32_e32 v203, v237, v246, vcc
	v_cndmask_b32_e32 v202, v231, v242, vcc
	v_pk_fma_f32 v[198:199], v[128:129], v[198:199], v[200:201]
	v_cndmask_b32_e64 v201, v247, v239, s[42:43]
	v_cndmask_b32_e64 v200, v243, v234, s[42:43]
	v_pk_fma_f32 v[122:123], v[122:123], v[202:203], v[134:135]
	v_cndmask_b32_e32 v135, v213, v236, vcc
	v_pk_fma_f32 v[122:123], v[126:127], v[200:201], v[122:123]
	v_cndmask_b32_e32 v134, v0, v230, vcc
	v_mul_f32_e32 v158, 0xbfb8aa3b, v156
	v_mul_f32_e32 v159, 0xbfb8aa3b, v157
	v_mul_f32_e32 v172, 0xbfb8aa3b, v170
	v_mul_f32_e32 v173, 0xbfb8aa3b, v171
	v_pk_fma_f32 v[122:123], v[176:177], v[130:131], v[122:123]
	v_cndmask_b32_e64 v131, v238, v227, s[42:43]
	v_cndmask_b32_e64 v130, v232, v151, s[42:43]
	v_pk_fma_f32 v[124:125], v[124:125], v[134:135], v[136:137]
	v_exp_f32_e32 v158, v158
	v_exp_f32_e32 v159, v159
	v_exp_f32_e32 v172, v172
	v_exp_f32_e32 v173, v173
	v_pk_fma_f32 v[124:125], v[128:129], v[130:131], v[124:125]
	v_mov_b32_e32 v179, v178
	v_pk_fma_f32 v[124:125], v[174:175], v[132:133], v[124:125]
	v_mov_b32_e32 v183, v182
	v_mul_f32_e32 v0, 0xbfb8aa3b, v124
	v_exp_f32_e32 v0, v0
	v_mul_f32_e32 v128, 0xbfb8aa3b, v125
	v_mov_b32_e32 v130, v178
	v_mov_b32_e32 v131, v178
	v_add_f32_e32 v158, 1.0, v158
	v_add_f32_e32 v159, 1.0, v159
	v_add_f32_e32 v172, 1.0, v172
	v_add_f32_e32 v173, 1.0, v173
	v_exp_f32_e32 v129, v128
	v_pk_mul_f32 v[104:105], v[104:105], v[130:131]
	v_pk_mul_f32 v[102:103], v[102:103], v[178:179]
	v_pk_mul_f32 v[98:99], v[98:99], v[182:183]
	s_nop 1
	v_rcp_f32_e32 v158, v158
	v_rcp_f32_e32 v159, v159
	v_rcp_f32_e32 v172, v172
	v_rcp_f32_e32 v173, v173
	v_mov_b32_e32 v130, v182
	v_mov_b32_e32 v131, v182
	s_nop 1
	v_mov_b32_dpp v177, v102 row_ror:2 row_mask:0xf bank_mask:0xf
	s_nop 1
	v_mov_b32_dpp v179, v103 row_ror:2 row_mask:0xf bank_mask:0xf
	s_nop 1
	v_mov_b32_dpp v183, v104 row_ror:2 row_mask:0xf bank_mask:0xf
	s_nop 1
	v_mov_b32_dpp v201, v105 row_ror:2 row_mask:0xf bank_mask:0xf
	v_pk_fma_f32 v[188:189], v[188:189], v[132:133], v[198:199]
	v_pk_mul_f32 v[100:101], v[100:101], v[130:131]
	v_mov_b32_dpp v176, v102 row_ror:1 row_mask:0xf bank_mask:0xf
	v_mov_b32_dpp v178, v103 row_ror:1 row_mask:0xf bank_mask:0xf
	v_mov_b32_dpp v182, v104 row_ror:1 row_mask:0xf bank_mask:0xf
	v_mov_b32_dpp v200, v105 row_ror:1 row_mask:0xf bank_mask:0xf
	v_cndmask_b32_e32 v130, v194, v177, vcc
	v_cndmask_b32_e32 v131, v195, v179, vcc
	v_cndmask_b32_e32 v132, v196, v183, vcc
	v_cndmask_b32_e32 v133, v197, v201, vcc
	v_mul_f32_e32 v186, 0xbfb8aa3b, v184
	v_mul_f32_e32 v187, 0xbfb8aa3b, v185
	v_mul_f32_e32 v198, 0xbfb8aa3b, v188
	v_mul_f32_e32 v199, 0xbfb8aa3b, v189
	v_add_f32_e32 v0, 1.0, v0
	v_cndmask_b32_e64 v134, v176, v190, s[42:43]
	v_cndmask_b32_e64 v135, v178, v191, s[42:43]
	v_cndmask_b32_e64 v136, v182, v192, s[42:43]
	v_cndmask_b32_e64 v137, v200, v193, s[42:43]
	s_waitcnt vmcnt(1)
	v_pk_fma_f32 v[132:133], v[116:117], v[132:133], v[120:121]
	v_pk_fma_f32 v[130:131], v[114:115], v[130:131], v[118:119]
	v_exp_f32_e32 v186, v186
	v_exp_f32_e32 v187, v187
	v_exp_f32_e32 v198, v198
	v_exp_f32_e32 v199, v199
	v_rcp_f32_e32 v128, v0
	v_add_f32_e32 v0, 1.0, v129
	v_pk_fma_f32 v[132:133], v[112:113], v[136:137], v[132:133]
	v_pk_fma_f32 v[130:131], v[110:111], v[134:135], v[130:131]
	v_rcp_f32_e32 v129, v0
	v_or_b32_e32 v0, 16, v150
	v_or_b32_e32 v174, 32, v150
	v_or_b32_e32 v175, 48, v150
	v_pk_mul_f32 v[150:151], v[156:157], v[158:159]
	v_pk_mul_f32 v[156:157], v[170:171], v[172:173]
	v_pk_fma_f32 v[104:105], v[104:105], v[108:109], v[132:133]
	v_pk_fma_f32 v[102:103], v[102:103], v[106:107], v[130:131]
	v_pk_mul_f32 v[104:105], v[156:157], v[104:105]
	v_pk_mul_f32 v[102:103], v[150:151], v[102:103]
	v_add_f32_e32 v186, 1.0, v186
	v_cvt_pk_bf16_f32 v102, v102, v103
	v_cvt_pk_bf16_f32 v103, v104, v105
	v_mov_b64_e32 v[104:105], s[36:37]
	v_add_f32_e32 v187, 1.0, v187
	v_add_f32_e32 v198, 1.0, v198
	v_add_f32_e32 v199, 1.0, v199
	v_mad_i64_i32 v[130:131], s[0:1], v0, s46, v[104:105]
	v_lshlrev_b64 v[132:133], 1, v[180:181]
	s_nop 1
	v_rcp_f32_e32 v186, v186
	v_rcp_f32_e32 v187, v187
	v_rcp_f32_e32 v198, v198
	v_rcp_f32_e32 v199, v199
	v_lshl_add_u64 v[130:131], v[130:131], 0, v[132:133]
	s_nop 1
	v_mov_b32_dpp v158, v98 row_ror:2 row_mask:0xf bank_mask:0xf
	s_nop 1
	v_mov_b32_dpp v170, v99 row_ror:2 row_mask:0xf bank_mask:0xf
	s_nop 1
	v_mov_b32_dpp v172, v100 row_ror:2 row_mask:0xf bank_mask:0xf
	s_nop 1
	v_mov_b32_dpp v180, v101 row_ror:2 row_mask:0xf bank_mask:0xf
	global_store_dwordx2 v[130:131], v[102:103], off
	v_mov_b32_dpp v0, v98 row_ror:1 row_mask:0xf bank_mask:0xf
	v_mov_b32_dpp v159, v99 row_ror:1 row_mask:0xf bank_mask:0xf
	v_mov_b32_dpp v171, v100 row_ror:1 row_mask:0xf bank_mask:0xf
	v_mov_b32_dpp v173, v101 row_ror:1 row_mask:0xf bank_mask:0xf
	v_cndmask_b32_e32 v102, v177, v158, vcc
	v_cndmask_b32_e32 v103, v179, v170, vcc
	v_cndmask_b32_e32 v130, v183, v172, vcc
	v_cndmask_b32_e32 v131, v201, v180, vcc
	v_cndmask_b32_e64 v134, v0, v176, s[42:43]
	v_cndmask_b32_e64 v135, v159, v178, s[42:43]
	v_cndmask_b32_e64 v136, v171, v182, s[42:43]
	v_cndmask_b32_e64 v137, v173, v200, s[42:43]
	v_pk_fma_f32 v[130:131], v[116:117], v[130:131], v[120:121]
	v_pk_fma_f32 v[102:103], v[114:115], v[102:103], v[118:119]
	v_mul_f32_e32 v126, 0xbfb8aa3b, v122
	v_mul_f32_e32 v127, 0xbfb8aa3b, v123
	v_pk_fma_f32 v[130:131], v[112:113], v[136:137], v[130:131]
	v_pk_fma_f32 v[102:103], v[110:111], v[134:135], v[102:103]
	v_exp_f32_e32 v126, v126
	v_exp_f32_e32 v127, v127
	v_pk_mul_f32 v[150:151], v[184:185], v[186:187]
	v_pk_mul_f32 v[156:157], v[188:189], v[198:199]
	v_pk_fma_f32 v[100:101], v[100:101], v[108:109], v[130:131]
	v_pk_fma_f32 v[98:99], v[98:99], v[106:107], v[102:103]
	v_pk_mul_f32 v[100:101], v[156:157], v[100:101]
	v_pk_mul_f32 v[98:99], v[150:151], v[98:99]
	v_add_f32_e32 v126, 1.0, v126
	v_cvt_pk_bf16_f32 v98, v98, v99
	v_cvt_pk_bf16_f32 v99, v100, v101
	v_mad_i64_i32 v[100:101], s[0:1], v174, s46, v[104:105]
	v_lshl_add_u64 v[100:101], v[100:101], 0, v[132:133]
	v_add_f32_e32 v127, 1.0, v127
	global_store_dwordx2 v[100:101], v[98:99], off
	s_nop 1
	v_rcp_f32_e32 v126, v126
	v_rcp_f32_e32 v127, v127
	s_nop 1
	v_mov_b32_dpp v98, v154 row_ror:2 row_mask:0xf bank_mask:0xf
	s_nop 1
	v_mov_b32_dpp v99, v155 row_ror:2 row_mask:0xf bank_mask:0xf
	s_nop 1
	v_mov_b32_dpp v100, v152 row_ror:2 row_mask:0xf bank_mask:0xf
	s_nop 1
	v_mov_b32_dpp v101, v153 row_ror:2 row_mask:0xf bank_mask:0xf
	v_mov_b32_dpp v102, v154 row_ror:1 row_mask:0xf bank_mask:0xf
	v_mov_b32_dpp v103, v155 row_ror:1 row_mask:0xf bank_mask:0xf
	v_mov_b32_dpp v130, v152 row_ror:1 row_mask:0xf bank_mask:0xf
	v_mov_b32_dpp v131, v153 row_ror:1 row_mask:0xf bank_mask:0xf
	v_cndmask_b32_e32 v98, v158, v98, vcc
	v_cndmask_b32_e32 v99, v170, v99, vcc
	v_cndmask_b32_e32 v100, v172, v100, vcc
	v_cndmask_b32_e32 v101, v180, v101, vcc
	v_cndmask_b32_e64 v102, v102, v0, s[42:43]
	v_cndmask_b32_e64 v103, v103, v159, s[42:43]
	v_cndmask_b32_e64 v130, v130, v171, s[42:43]
	v_cndmask_b32_e64 v131, v131, v173, s[42:43]
	v_pk_fma_f32 v[98:99], v[114:115], v[98:99], v[118:119]
	v_pk_fma_f32 v[100:101], v[116:117], v[100:101], v[120:121]
	v_pk_fma_f32 v[98:99], v[110:111], v[102:103], v[98:99]
	v_pk_fma_f32 v[100:101], v[112:113], v[130:131], v[100:101]
	v_pk_mul_f32 v[122:123], v[122:123], v[126:127]
	v_pk_mul_f32 v[124:125], v[124:125], v[128:129]
	v_pk_fma_f32 v[98:99], v[154:155], v[106:107], v[98:99]
	v_pk_fma_f32 v[100:101], v[152:153], v[108:109], v[100:101]
	v_pk_mul_f32 v[98:99], v[122:123], v[98:99]
	v_pk_mul_f32 v[100:101], v[124:125], v[100:101]
	v_cvt_pk_bf16_f32 v98, v98, v99
	s_nop 0
	v_cvt_pk_bf16_f32 v99, v100, v101
	v_mad_i64_i32 v[100:101], s[0:1], v175, s46, v[104:105]
	v_lshl_add_u64 v[100:101], v[100:101], 0, v[132:133]
	global_store_dwordx2 v[100:101], v[98:99], off
	s_add_i32 s0, s6, 2
	v_and_b32_e32 v129, 15, v226
	v_or_b32_e32 v106, s4, v129
	v_ashrrev_i32_e32 v107, 31, v106
	v_lshl_add_u64 v[104:105], v[106:107], 3, s[38:39]
	global_load_dwordx2 v[108:109], v[104:105], off offset:1024
	global_load_dwordx2 v[102:103], v[104:105], off offset:1152
	global_load_dwordx2 v[100:101], v[104:105], off offset:1280
	s_nop 0
	global_load_dwordx2 v[104:105], v[104:105], off offset:1408
	v_ashrrev_i32_e32 v0, 1, v226
	v_and_b32_e32 v0, -8, v0
	v_add_u32_e32 v98, s21, v0
	s_mul_hi_i32 s1, s0, 0xb000
	s_mul_i32 s0, s0, 0xb000
	s_add_u32 s0, s18, s0
	s_addc_u32 s1, s19, s1
	s_add_u32 s78, s0, s80
	s_addc_u32 s79, s1, s81
	s_waitcnt vmcnt(3)
	v_ffbh_u32_e32 v0, v109
	v_min_u32_e32 v0, 32, v0
	v_lshlrev_b64 v[108:109], v0, v[108:109]
	v_min_u32_e32 v99, 1, v108
	v_or_b32_e32 v99, v109, v99
	v_cvt_f32_u32_e32 v99, v99
	v_sub_u32_e32 v0, 32, v0
	v_ldexp_f32 v0, v99, v0
	v_mul_f32_e32 v0, 0x33800000, v0
	v_fmamk_f32 v0, v0, 0x3a800000, v210
	s_nop 0
	v_rsq_f32_e32 v0, v0
	s_nop 0
	s_nop 0
	v_ashrrev_i32_e32 v99, 31, v98
	v_pk_mul_f32 v[118:119], v[96:97], v[0:1] op_sel_hi:[1,0]
	v_pk_mul_f32 v[116:117], v[94:95], v[0:1] op_sel_hi:[1,0]
	v_pk_mul_f32 v[112:113], v[92:93], v[0:1] op_sel_hi:[1,0]
	v_pk_mul_f32 v[114:115], v[90:91], v[0:1] op_sel_hi:[1,0]
	v_lshl_add_u64 v[90:91], v[98:99], 1, s[78:79]
	v_cmp_gt_u32_e32 vcc, 2, v129
	s_and_saveexec_b64 s[0:1], vcc
	s_cbranch_execz .LBB0_117
	v_mul_u32_u24_e32 v0, 0x1600, v129
	v_lshlrev_b32_e32 v0, 1, v0
	v_cvt_pk_bf16_f32 v92, v116, v117
	v_cvt_pk_bf16_f32 v93, v118, v119
	v_lshl_add_u64 v[96:97], v[90:91], 0, v[0:1]
	v_cvt_pk_bf16_f32 v94, v114, v115
	v_cvt_pk_bf16_f32 v95, v112, v113
	global_store_dwordx2 v[96:97], v[92:93], off
	global_store_dwordx2 v[96:97], v[94:95], off offset:256

.LBB0_119:
	s_or_b64 exec, exec, s[0:1]
	v_ffbh_u32_e32 v0, v103
	v_min_u32_e32 v0, 32, v0
	v_lshlrev_b64 v[82:83], v0, v[102:103]
	v_min_u32_e32 v82, 1, v82
	v_or_b32_e32 v82, v83, v82
	v_cvt_f32_u32_e32 v82, v82
	v_sub_u32_e32 v0, 32, v0
	v_add_u32_e32 v126, s5, v98
	v_ldexp_f32 v0, v82, v0
	v_mul_f32_e32 v0, 0x33800000, v0
	v_fmamk_f32 v0, v0, 0x3a800000, v210
	s_nop 0
	v_rsq_f32_e32 v0, v0
	s_nop 0
	s_nop 0
	v_mov_b32_e32 v124, v0
	v_ffbh_u32_e32 v0, v101
	v_min_u32_e32 v0, 32, v0
	v_pk_mul_f32 v[132:133], v[78:79], v[124:125] op_sel_hi:[1,0]
	v_lshlrev_b64 v[78:79], v0, v[100:101]
	v_min_u32_e32 v78, 1, v78
	v_or_b32_e32 v78, v79, v78
	v_cvt_f32_u32_e32 v78, v78
	v_sub_u32_e32 v0, 32, v0
	v_pk_mul_f32 v[130:131], v[80:81], v[124:125] op_sel_hi:[1,0]
	v_ldexp_f32 v0, v78, v0
	v_mul_f32_e32 v0, 0x33800000, v0
	v_fmamk_f32 v0, v0, 0x3a800000, v210
	s_nop 0
	v_rsq_f32_e32 v0, v0
	s_nop 0
	s_nop 0
	v_mov_b32_e32 v128, v0
	v_pk_mul_f32 v[134:135], v[76:77], v[128:129] op_sel_hi:[1,0]
	v_pk_mul_f32 v[156:157], v[74:75], v[128:129] op_sel_hi:[1,0]
	v_ashrrev_i32_e32 v127, 31, v126
	v_lshlrev_b64 v[86:87], 2, v[126:127]
	v_lshl_add_u64 v[74:75], s[44:45], 0, v[86:87]
	v_lshl_add_u64 v[76:77], s[60:61], 0, v[86:87]
	global_load_dwordx4 v[90:93], v[74:75], off
	global_load_dwordx4 v[94:97], v[76:77], off
	v_lshl_add_u64 v[74:75], s[2:3], 0, v[86:87]
	global_load_dwordx4 v[98:101], v[74:75], off
	v_lshl_add_u64 v[74:75], s[48:49], 0, v[86:87]
	global_load_dwordx4 v[102:105], v[74:75], off
	s_nop 1
	v_cmp_lt_u32_e32 vcc, 1, v129
	v_mov_b32_dpp v174, v116 row_ror:1 row_mask:0xf bank_mask:0xf
	v_mov_b32_dpp v172, v116 row_ror:2 row_mask:0xf bank_mask:0xf
	v_mov_b32_dpp v175, v117 row_ror:1 row_mask:0xf bank_mask:0xf
	v_mov_b32_dpp v173, v117 row_ror:2 row_mask:0xf bank_mask:0xf
	v_mov_b32_dpp v170, v118 row_ror:1 row_mask:0xf bank_mask:0xf
	v_mov_b32_dpp v158, v118 row_ror:2 row_mask:0xf bank_mask:0xf
	v_mov_b32_dpp v171, v119 row_ror:1 row_mask:0xf bank_mask:0xf
	v_mov_b32_dpp v159, v119 row_ror:2 row_mask:0xf bank_mask:0xf
	v_mov_b32_dpp v191, v132 row_ror:1 row_mask:0xf bank_mask:0xf
	v_mov_b32_dpp v190, v132 row_ror:2 row_mask:0xf bank_mask:0xf
	v_mov_b32_dpp v195, v133 row_ror:1 row_mask:0xf bank_mask:0xf
	v_mov_b32_dpp v194, v133 row_ror:2 row_mask:0xf bank_mask:0xf
	v_mov_b32_dpp v179, v130 row_ror:1 row_mask:0xf bank_mask:0xf
	v_mov_b32_dpp v178, v130 row_ror:2 row_mask:0xf bank_mask:0xf
	v_mov_b32_dpp v185, v131 row_ror:1 row_mask:0xf bank_mask:0xf
	v_mov_b32_dpp v183, v131 row_ror:2 row_mask:0xf bank_mask:0xf
	v_mov_b32_dpp v184, v156 row_ror:1 row_mask:0xf bank_mask:0xf
	v_mov_b32_dpp v181, v156 row_ror:2 row_mask:0xf bank_mask:0xf
	v_mov_b32_dpp v189, v157 row_ror:1 row_mask:0xf bank_mask:0xf
	v_mov_b32_dpp v187, v157 row_ror:2 row_mask:0xf bank_mask:0xf
	v_mov_b32_dpp v107, v134 row_ror:1 row_mask:0xf bank_mask:0xf
	v_mov_b32_dpp v0, v134 row_ror:2 row_mask:0xf bank_mask:0xf
	v_mov_b32_dpp v177, v135 row_ror:1 row_mask:0xf bank_mask:0xf
	v_mov_b32_dpp v176, v135 row_ror:2 row_mask:0xf bank_mask:0xf
	v_mov_b32_dpp v193, v122 row_ror:1 row_mask:0xf bank_mask:0xf
	v_mov_b32_dpp v192, v122 row_ror:2 row_mask:0xf bank_mask:0xf
	v_mov_b32_dpp v197, v123 row_ror:1 row_mask:0xf bank_mask:0xf
	v_mov_b32_dpp v196, v123 row_ror:2 row_mask:0xf bank_mask:0xf
	v_mov_b32_dpp v182, v120 row_ror:1 row_mask:0xf bank_mask:0xf
	v_mov_b32_dpp v180, v120 row_ror:2 row_mask:0xf bank_mask:0xf
	v_mov_b32_dpp v188, v121 row_ror:1 row_mask:0xf bank_mask:0xf
	v_mov_b32_dpp v186, v121 row_ror:2 row_mask:0xf bank_mask:0xf
	v_lshl_add_u64 v[74:75], s[96:97], 0, v[86:87]
	v_lshl_add_u64 v[76:77], s[62:63], 0, v[86:87]
	global_load_dwordx4 v[82:85], v[74:75], off
	global_load_dwordx4 v[78:81], v[76:77], off
	v_lshl_add_u64 v[74:75], s[64:65], 0, v[86:87]
	v_lshl_add_u64 v[86:87], s[66:67], 0, v[86:87]
	global_load_dwordx4 v[74:77], v[74:75], off
	s_nop 1
	global_load_dwordx4 v[86:89], v[86:87], off
	s_nop 1
	v_mov_b32_dpp v136, v114 row_ror:1 row_mask:0xf bank_mask:0xf
	v_mov_b32_dpp v152, v114 row_ror:2 row_mask:0xf bank_mask:0xf
	v_mov_b32_dpp v137, v115 row_ror:1 row_mask:0xf bank_mask:0xf
	v_mov_b32_dpp v153, v115 row_ror:2 row_mask:0xf bank_mask:0xf
	v_mov_b32_dpp v150, v112 row_ror:1 row_mask:0xf bank_mask:0xf
	v_mov_b32_dpp v154, v112 row_ror:2 row_mask:0xf bank_mask:0xf
	v_mov_b32_dpp v151, v113 row_ror:1 row_mask:0xf bank_mask:0xf
	v_mov_b32_dpp v155, v113 row_ror:2 row_mask:0xf bank_mask:0xf
	s_and_saveexec_b64 s[0:1], vcc
	s_cbranch_execz .Lcg_skip1
	s_waitcnt vmcnt(4)
	v_pk_fma_f32 v[198:199], v[92:93], v[158:159], v[104:105]
	s_nop 0
	v_pk_fma_f32 v[198:199], v[96:97], v[170:171], v[198:199]
	s_nop 0
	v_pk_fma_f32 v[118:119], v[118:119], v[100:101], v[198:199]
	v_pk_fma_f32 v[198:199], v[90:91], v[172:173], v[102:103]
	v_mul_f32_e32 v125, 0xbfb8aa3b, v119
	v_exp_f32_e32 v125, v125
	v_pk_fma_f32 v[198:199], v[94:95], v[174:175], v[198:199]
	v_mul_f32_e32 v200, 0xbfb8aa3b, v118
	v_pk_fma_f32 v[116:117], v[116:117], v[98:99], v[198:199]
	v_add_f32_e32 v125, 1.0, v125
	v_rcp_f32_e32 v201, v125
	v_mul_f32_e32 v125, 0xbfb8aa3b, v117
	v_exp_f32_e32 v125, v125
	v_mul_f32_e32 v198, 0xbfb8aa3b, v116
	v_exp_f32_e32 v200, v200
	v_exp_f32_e32 v198, v198
	v_add_f32_e32 v125, 1.0, v125
	v_rcp_f32_e32 v199, v125
	v_add_f32_e32 v200, 1.0, v200
	v_add_f32_e32 v125, 1.0, v198
	v_rcp_f32_e32 v198, v125
	v_rcp_f32_e32 v200, v200
	v_add_u32_e32 v125, 0x80, v106
	v_pk_mul_f32 v[116:117], v[116:117], v[198:199]
	v_pk_mul_f32 v[118:119], v[118:119], v[200:201]
	s_waitcnt vmcnt(0)
	v_pk_fma_f32 v[198:199], v[84:85], v[154:155], v[88:89]
	v_pk_fma_f32 v[200:201], v[82:83], v[152:153], v[86:87]
	v_pk_fma_f32 v[198:199], v[80:81], v[150:151], v[198:199]
	v_pk_fma_f32 v[200:201], v[78:79], v[136:137], v[200:201]
	v_pk_fma_f32 v[112:113], v[112:113], v[76:77], v[198:199]
	v_pk_fma_f32 v[114:115], v[114:115], v[74:75], v[200:201]
	v_pk_mul_f32 v[112:113], v[118:119], v[112:113]
	v_pk_mul_f32 v[114:115], v[116:117], v[114:115]
	s_nop 0
	v_cvt_pk_bf16_f32 v114, v114, v115
	v_cvt_pk_bf16_f32 v115, v112, v113
	v_mov_b64_e32 v[112:113], s[36:37]
	v_mad_i64_i32 v[112:113], s[6:7], v125, s46, v[112:113]
	v_lshl_add_u64 v[112:113], v[126:127], 1, v[112:113]
	global_store_dwordx2 v[112:113], v[114:115], off
.LBB0_121:
	s_or_b64 exec, exec, s[0:1]
	v_cmp_eq_u32_e64 s[42:43], 0, v129
	v_cndmask_b32_e32 v115, v173, v194, vcc
	v_cndmask_b32_e32 v114, v172, v190, vcc
	v_cndmask_b32_e64 v113, v195, v175, s[42:43]
	v_cndmask_b32_e64 v112, v191, v174, s[42:43]
	s_waitcnt vmcnt(4)
	v_pk_fma_f32 v[114:115], v[90:91], v[114:115], v[102:103]
	v_cndmask_b32_e32 v119, v159, v183, vcc
	v_cndmask_b32_e32 v118, v158, v178, vcc
	v_pk_fma_f32 v[112:113], v[94:95], v[112:113], v[114:115]
	v_cndmask_b32_e64 v117, v185, v171, s[42:43]
	v_cndmask_b32_e64 v116, v179, v170, s[42:43]
	v_pk_fma_f32 v[118:119], v[92:93], v[118:119], v[104:105]
	v_pk_fma_f32 v[112:113], v[132:133], v[98:99], v[112:113]
	v_pk_fma_f32 v[116:117], v[96:97], v[116:117], v[118:119]
	v_cndmask_b32_e32 v133, v194, v187, vcc
	v_cndmask_b32_e32 v132, v190, v181, vcc
	v_pk_fma_f32 v[116:117], v[130:131], v[100:101], v[116:117]
	v_cndmask_b32_e64 v131, v189, v195, s[42:43]
	v_cndmask_b32_e64 v130, v184, v191, s[42:43]
	v_pk_fma_f32 v[132:133], v[90:91], v[132:133], v[102:103]
	v_cndmask_b32_e32 v159, v183, v176, vcc
	v_pk_fma_f32 v[130:131], v[94:95], v[130:131], v[132:133]
	v_cndmask_b32_e32 v158, v178, v0, vcc
	v_pk_fma_f32 v[130:131], v[156:157], v[98:99], v[130:131]
	v_cndmask_b32_e64 v157, v177, v185, s[42:43]
	v_cndmask_b32_e64 v156, v107, v179, s[42:43]
	v_pk_fma_f32 v[158:159], v[92:93], v[158:159], v[104:105]
	v_cndmask_b32_e32 v171, v187, v196, vcc
	v_cndmask_b32_e32 v170, v181, v192, vcc
	v_pk_fma_f32 v[156:157], v[96:97], v[156:157], v[158:159]
	v_cndmask_b32_e64 v159, v197, v189, s[42:43]
	v_cndmask_b32_e64 v158, v193, v184, s[42:43]
	v_pk_fma_f32 v[90:91], v[90:91], v[170:171], v[102:103]
	v_cndmask_b32_e32 v103, v176, v186, vcc
	v_pk_fma_f32 v[90:91], v[94:95], v[158:159], v[90:91]
	v_cndmask_b32_e32 v102, v0, v180, vcc
	v_mul_f32_e32 v114, 0xbfb8aa3b, v112
	v_mul_f32_e32 v115, 0xbfb8aa3b, v113
	v_mul_f32_e32 v118, 0xbfb8aa3b, v116
	v_mul_f32_e32 v119, 0xbfb8aa3b, v117
	v_pk_fma_f32 v[90:91], v[122:123], v[98:99], v[90:91]
	v_cndmask_b32_e64 v99, v188, v177, s[42:43]
	v_cndmask_b32_e64 v98, v182, v107, s[42:43]
	v_pk_fma_f32 v[92:93], v[92:93], v[102:103], v[104:105]
	v_exp_f32_e32 v114, v114
	v_exp_f32_e32 v115, v115
	v_exp_f32_e32 v118, v118
	v_exp_f32_e32 v119, v119
	v_pk_fma_f32 v[92:93], v[96:97], v[98:99], v[92:93]
	v_mov_b32_e32 v125, v124
	v_pk_fma_f32 v[92:93], v[120:121], v[100:101], v[92:93]
	v_mov_b32_e32 v129, v128
	v_mul_f32_e32 v0, 0xbfb8aa3b, v92
	v_exp_f32_e32 v0, v0
	v_mul_f32_e32 v96, 0xbfb8aa3b, v93
	v_mov_b32_e32 v98, v124
	v_mov_b32_e32 v99, v124
	v_add_f32_e32 v114, 1.0, v114
	v_add_f32_e32 v115, 1.0, v115
	v_add_f32_e32 v118, 1.0, v118
	v_add_f32_e32 v119, 1.0, v119
	v_exp_f32_e32 v97, v96
	v_pk_mul_f32 v[72:73], v[72:73], v[98:99]
	v_pk_mul_f32 v[70:71], v[70:71], v[124:125]
	v_pk_mul_f32 v[66:67], v[66:67], v[128:129]
	s_nop 1
	v_rcp_f32_e32 v114, v114
	v_rcp_f32_e32 v115, v115
	v_rcp_f32_e32 v118, v118
	v_rcp_f32_e32 v119, v119
	v_mov_b32_e32 v98, v128
	v_mov_b32_e32 v99, v128
	s_nop 1
	v_mov_b32_dpp v123, v70 row_ror:2 row_mask:0xf bank_mask:0xf
	s_nop 1
	v_mov_b32_dpp v125, v71 row_ror:2 row_mask:0xf bank_mask:0xf
	s_nop 1
	v_mov_b32_dpp v129, v72 row_ror:2 row_mask:0xf bank_mask:0xf
	s_nop 1
	v_mov_b32_dpp v159, v73 row_ror:2 row_mask:0xf bank_mask:0xf
	v_pk_fma_f32 v[134:135], v[134:135], v[100:101], v[156:157]
	v_pk_mul_f32 v[68:69], v[68:69], v[98:99]
	v_mov_b32_dpp v122, v70 row_ror:1 row_mask:0xf bank_mask:0xf
	v_mov_b32_dpp v124, v71 row_ror:1 row_mask:0xf bank_mask:0xf
	v_mov_b32_dpp v128, v72 row_ror:1 row_mask:0xf bank_mask:0xf
	v_mov_b32_dpp v158, v73 row_ror:1 row_mask:0xf bank_mask:0xf
	v_cndmask_b32_e32 v98, v152, v123, vcc
	v_cndmask_b32_e32 v99, v153, v125, vcc
	v_cndmask_b32_e32 v100, v154, v129, vcc
	v_cndmask_b32_e32 v101, v155, v159, vcc
	v_mul_f32_e32 v132, 0xbfb8aa3b, v130
	v_mul_f32_e32 v133, 0xbfb8aa3b, v131
	v_mul_f32_e32 v156, 0xbfb8aa3b, v134
	v_mul_f32_e32 v157, 0xbfb8aa3b, v135
	v_add_f32_e32 v0, 1.0, v0
	v_cndmask_b32_e64 v102, v122, v136, s[42:43]
	v_cndmask_b32_e64 v103, v124, v137, s[42:43]
	v_cndmask_b32_e64 v104, v128, v150, s[42:43]
	v_cndmask_b32_e64 v105, v158, v151, s[42:43]
	s_waitcnt vmcnt(1)
	v_pk_fma_f32 v[100:101], v[84:85], v[100:101], v[88:89]
	v_pk_fma_f32 v[98:99], v[82:83], v[98:99], v[86:87]
	v_exp_f32_e32 v132, v132
	v_exp_f32_e32 v133, v133
	v_exp_f32_e32 v156, v156
	v_exp_f32_e32 v157, v157
	v_rcp_f32_e32 v96, v0
	v_add_f32_e32 v0, 1.0, v97
	v_pk_fma_f32 v[100:101], v[80:81], v[104:105], v[100:101]
	v_pk_fma_f32 v[98:99], v[78:79], v[102:103], v[98:99]
	v_rcp_f32_e32 v97, v0
	v_add_u32_e32 v0, 0x90, v106
	v_add_u32_e32 v120, 0xa0, v106
	v_add_u32_e32 v121, 0xb0, v106
	v_pk_mul_f32 v[106:107], v[112:113], v[114:115]
	v_pk_mul_f32 v[112:113], v[116:117], v[118:119]
	v_pk_fma_f32 v[72:73], v[72:73], v[76:77], v[100:101]
	v_pk_fma_f32 v[70:71], v[70:71], v[74:75], v[98:99]
	v_pk_mul_f32 v[72:73], v[112:113], v[72:73]
	v_pk_mul_f32 v[70:71], v[106:107], v[70:71]
	v_add_f32_e32 v132, 1.0, v132
	v_cvt_pk_bf16_f32 v70, v70, v71
	v_cvt_pk_bf16_f32 v71, v72, v73
	v_mov_b64_e32 v[72:73], s[36:37]
	v_add_f32_e32 v133, 1.0, v133
	v_add_f32_e32 v156, 1.0, v156
	v_add_f32_e32 v157, 1.0, v157
	v_mad_i64_i32 v[98:99], s[0:1], v0, s46, v[72:73]
	v_lshlrev_b64 v[100:101], 1, v[126:127]
	s_nop 1
	v_rcp_f32_e32 v132, v132
	v_rcp_f32_e32 v133, v133
	v_rcp_f32_e32 v156, v156
	v_rcp_f32_e32 v157, v157
	v_lshl_add_u64 v[98:99], v[98:99], 0, v[100:101]
	s_nop 1
	v_mov_b32_dpp v114, v66 row_ror:2 row_mask:0xf bank_mask:0xf
	s_nop 1
	v_mov_b32_dpp v116, v67 row_ror:2 row_mask:0xf bank_mask:0xf
	s_nop 1
	v_mov_b32_dpp v118, v68 row_ror:2 row_mask:0xf bank_mask:0xf
	s_nop 1
	v_mov_b32_dpp v126, v69 row_ror:2 row_mask:0xf bank_mask:0xf
	global_store_dwordx2 v[98:99], v[70:71], off
	v_mov_b32_dpp v0, v66 row_ror:1 row_mask:0xf bank_mask:0xf
	v_mov_b32_dpp v115, v67 row_ror:1 row_mask:0xf bank_mask:0xf
	v_mov_b32_dpp v117, v68 row_ror:1 row_mask:0xf bank_mask:0xf
	v_mov_b32_dpp v119, v69 row_ror:1 row_mask:0xf bank_mask:0xf
	v_cndmask_b32_e32 v70, v123, v114, vcc
	v_cndmask_b32_e32 v71, v125, v116, vcc
	v_cndmask_b32_e32 v98, v129, v118, vcc
	v_cndmask_b32_e32 v99, v159, v126, vcc
	v_cndmask_b32_e64 v102, v0, v122, s[42:43]
	v_cndmask_b32_e64 v103, v115, v124, s[42:43]
	v_cndmask_b32_e64 v104, v117, v128, s[42:43]
	v_cndmask_b32_e64 v105, v119, v158, s[42:43]
	v_pk_fma_f32 v[98:99], v[84:85], v[98:99], v[88:89]
	v_pk_fma_f32 v[70:71], v[82:83], v[70:71], v[86:87]
	v_mul_f32_e32 v94, 0xbfb8aa3b, v90
	v_mul_f32_e32 v95, 0xbfb8aa3b, v91
	v_pk_fma_f32 v[98:99], v[80:81], v[104:105], v[98:99]
	v_pk_fma_f32 v[70:71], v[78:79], v[102:103], v[70:71]
	v_exp_f32_e32 v94, v94
	v_exp_f32_e32 v95, v95
	v_pk_mul_f32 v[106:107], v[130:131], v[132:133]
	v_pk_mul_f32 v[112:113], v[134:135], v[156:157]
	v_pk_fma_f32 v[68:69], v[68:69], v[76:77], v[98:99]
	v_pk_fma_f32 v[66:67], v[66:67], v[74:75], v[70:71]
	v_pk_mul_f32 v[68:69], v[112:113], v[68:69]
	v_pk_mul_f32 v[66:67], v[106:107], v[66:67]
	v_add_f32_e32 v94, 1.0, v94
	v_cvt_pk_bf16_f32 v66, v66, v67
	v_cvt_pk_bf16_f32 v67, v68, v69
	v_mad_i64_i32 v[68:69], s[0:1], v120, s46, v[72:73]
	v_lshl_add_u64 v[68:69], v[68:69], 0, v[100:101]
	v_add_f32_e32 v95, 1.0, v95
	global_store_dwordx2 v[68:69], v[66:67], off
	s_nop 1
	v_rcp_f32_e32 v94, v94
	v_rcp_f32_e32 v95, v95
	s_nop 1
	v_mov_b32_dpp v66, v110 row_ror:2 row_mask:0xf bank_mask:0xf
	s_nop 1
	v_mov_b32_dpp v67, v111 row_ror:2 row_mask:0xf bank_mask:0xf
	s_nop 1
	v_mov_b32_dpp v68, v108 row_ror:2 row_mask:0xf bank_mask:0xf
	s_nop 1
	v_mov_b32_dpp v69, v109 row_ror:2 row_mask:0xf bank_mask:0xf
	v_mov_b32_dpp v70, v110 row_ror:1 row_mask:0xf bank_mask:0xf
	v_mov_b32_dpp v71, v111 row_ror:1 row_mask:0xf bank_mask:0xf
	v_mov_b32_dpp v98, v108 row_ror:1 row_mask:0xf bank_mask:0xf
	v_mov_b32_dpp v99, v109 row_ror:1 row_mask:0xf bank_mask:0xf
	v_cndmask_b32_e32 v66, v114, v66, vcc
	v_cndmask_b32_e32 v67, v116, v67, vcc
	v_cndmask_b32_e32 v68, v118, v68, vcc
	v_cndmask_b32_e32 v69, v126, v69, vcc
	v_cndmask_b32_e64 v70, v70, v0, s[42:43]
	v_cndmask_b32_e64 v71, v71, v115, s[42:43]
	v_cndmask_b32_e64 v98, v98, v117, s[42:43]
	v_cndmask_b32_e64 v99, v99, v119, s[42:43]
	v_pk_fma_f32 v[66:67], v[82:83], v[66:67], v[86:87]
	v_pk_fma_f32 v[68:69], v[84:85], v[68:69], v[88:89]
	v_pk_fma_f32 v[66:67], v[78:79], v[70:71], v[66:67]
	v_pk_fma_f32 v[68:69], v[80:81], v[98:99], v[68:69]
	v_pk_mul_f32 v[90:91], v[90:91], v[94:95]
	v_pk_mul_f32 v[92:93], v[92:93], v[96:97]
	v_pk_fma_f32 v[66:67], v[110:111], v[74:75], v[66:67]
	v_pk_fma_f32 v[68:69], v[108:109], v[76:77], v[68:69]
	v_pk_mul_f32 v[66:67], v[90:91], v[66:67]
	v_pk_mul_f32 v[68:69], v[92:93], v[68:69]
	v_cvt_pk_bf16_f32 v66, v66, v67
	s_nop 0
	v_cvt_pk_bf16_f32 v67, v68, v69
	v_mad_i64_i32 v[68:69], s[0:1], v121, s46, v[72:73]
	v_lshl_add_u64 v[68:69], v[68:69], 0, v[100:101]
	global_store_dwordx2 v[68:69], v[66:67], off
	s_nop 0
	v_and_b32_e32 v97, 15, v226
	v_or_b32_e32 v74, s4, v97
	v_ashrrev_i32_e32 v75, 31, v74
	v_lshl_add_u64 v[72:73], v[74:75], 3, s[38:39]
	global_load_dwordx2 v[76:77], v[72:73], off
	global_load_dwordx2 v[70:71], v[72:73], off offset:128
	global_load_dwordx2 v[68:69], v[72:73], off offset:256
	s_nop 0
	global_load_dwordx2 v[72:73], v[72:73], off offset:384
	v_ashrrev_i32_e32 v0, 1, v226
	v_and_b32_e32 v0, -8, v0
	v_add_u32_e32 v66, s21, v0
	s_waitcnt vmcnt(3)
	v_ffbh_u32_e32 v0, v77
	v_min_u32_e32 v0, 32, v0
	v_lshlrev_b64 v[76:77], v0, v[76:77]
	v_min_u32_e32 v67, 1, v76
	v_or_b32_e32 v67, v77, v67
	v_cvt_f32_u32_e32 v67, v67
	v_sub_u32_e32 v0, 32, v0
	v_ldexp_f32 v0, v67, v0
	v_mul_f32_e32 v0, 0x33800000, v0
	v_fmamk_f32 v0, v0, 0x3a800000, v210
	s_nop 0
	v_rsq_f32_e32 v0, v0
	s_nop 0
	s_nop 0
	v_ashrrev_i32_e32 v67, 31, v66
	v_pk_mul_f32 v[92:93], v[64:65], v[0:1] op_sel_hi:[1,0]
	v_pk_mul_f32 v[90:91], v[62:63], v[0:1] op_sel_hi:[1,0]
	v_pk_mul_f32 v[86:87], v[60:61], v[0:1] op_sel_hi:[1,0]
	v_pk_mul_f32 v[88:89], v[58:59], v[0:1] op_sel_hi:[1,0]
	v_lshl_add_u64 v[58:59], v[66:67], 1, s[76:77]
	v_cmp_gt_u32_e32 vcc, 2, v97
	s_and_saveexec_b64 s[0:1], vcc
	s_cbranch_execz .LBB0_123
	v_mul_u32_u24_e32 v0, 0x1600, v97
	v_lshlrev_b32_e32 v0, 1, v0
	v_cvt_pk_bf16_f32 v60, v90, v91
	v_cvt_pk_bf16_f32 v61, v92, v93
	v_lshl_add_u64 v[64:65], v[58:59], 0, v[0:1]
	v_cvt_pk_bf16_f32 v62, v88, v89
	v_cvt_pk_bf16_f32 v63, v86, v87
	global_store_dwordx2 v[64:65], v[60:61], off offset:8
	global_store_dwordx2 v[64:65], v[62:63], off offset:264

.LBB0_125:
	s_or_b64 exec, exec, s[0:1]
	v_ffbh_u32_e32 v0, v71
	v_min_u32_e32 v0, 32, v0
	v_lshlrev_b64 v[50:51], v0, v[70:71]
	v_min_u32_e32 v50, 1, v50
	v_or_b32_e32 v50, v51, v50
	v_cvt_f32_u32_e32 v50, v50
	v_sub_u32_e32 v0, 32, v0
	s_or_b32 s5, s5, 4
	v_add_u32_e32 v94, s5, v66
	v_ldexp_f32 v0, v50, v0
	v_mul_f32_e32 v0, 0x33800000, v0
	v_fmamk_f32 v0, v0, 0x3a800000, v210
	s_nop 0
	v_rsq_f32_e32 v0, v0
	s_nop 0
	s_nop 0
	v_mov_b32_e32 v84, v0
	v_ffbh_u32_e32 v0, v69
	v_min_u32_e32 v0, 32, v0
	v_pk_mul_f32 v[100:101], v[46:47], v[84:85] op_sel_hi:[1,0]
	v_lshlrev_b64 v[46:47], v0, v[68:69]
	v_min_u32_e32 v46, 1, v46
	v_or_b32_e32 v46, v47, v46
	v_cvt_f32_u32_e32 v46, v46
	v_sub_u32_e32 v0, 32, v0
	v_pk_mul_f32 v[98:99], v[48:49], v[84:85] op_sel_hi:[1,0]
	v_ldexp_f32 v0, v46, v0
	v_mul_f32_e32 v0, 0x33800000, v0
	v_fmamk_f32 v0, v0, 0x3a800000, v210
	s_nop 0
	v_rsq_f32_e32 v0, v0
	s_nop 0
	s_nop 0
	v_mov_b32_e32 v96, v0
	v_pk_mul_f32 v[102:103], v[44:45], v[96:97] op_sel_hi:[1,0]
	v_pk_mul_f32 v[112:113], v[42:43], v[96:97] op_sel_hi:[1,0]
	v_ashrrev_i32_e32 v95, 31, v94
	v_lshlrev_b64 v[54:55], 2, v[94:95]
	v_lshl_add_u64 v[42:43], s[44:45], 0, v[54:55]
	v_lshl_add_u64 v[44:45], s[60:61], 0, v[54:55]
	global_load_dwordx4 v[58:61], v[42:43], off
	global_load_dwordx4 v[62:65], v[44:45], off
	v_lshl_add_u64 v[42:43], s[2:3], 0, v[54:55]
	global_load_dwordx4 v[66:69], v[42:43], off
	v_lshl_add_u64 v[42:43], s[48:49], 0, v[54:55]
	global_load_dwordx4 v[70:73], v[42:43], off
	s_nop 1
	v_cmp_lt_u32_e32 vcc, 1, v97
	v_mov_b32_dpp v120, v90 row_ror:1 row_mask:0xf bank_mask:0xf
	v_mov_b32_dpp v118, v90 row_ror:2 row_mask:0xf bank_mask:0xf
	v_mov_b32_dpp v121, v91 row_ror:1 row_mask:0xf bank_mask:0xf
	v_mov_b32_dpp v119, v91 row_ror:2 row_mask:0xf bank_mask:0xf
	v_mov_b32_dpp v116, v92 row_ror:1 row_mask:0xf bank_mask:0xf
	v_mov_b32_dpp v114, v92 row_ror:2 row_mask:0xf bank_mask:0xf
	v_mov_b32_dpp v117, v93 row_ror:1 row_mask:0xf bank_mask:0xf
	v_mov_b32_dpp v115, v93 row_ror:2 row_mask:0xf bank_mask:0xf
	v_mov_b32_dpp v137, v100 row_ror:1 row_mask:0xf bank_mask:0xf
	v_mov_b32_dpp v136, v100 row_ror:2 row_mask:0xf bank_mask:0xf
	v_mov_b32_dpp v153, v101 row_ror:1 row_mask:0xf bank_mask:0xf
	v_mov_b32_dpp v152, v101 row_ror:2 row_mask:0xf bank_mask:0xf
	v_mov_b32_dpp v125, v98 row_ror:1 row_mask:0xf bank_mask:0xf
	v_mov_b32_dpp v124, v98 row_ror:2 row_mask:0xf bank_mask:0xf
	v_mov_b32_dpp v131, v99 row_ror:1 row_mask:0xf bank_mask:0xf
	v_mov_b32_dpp v129, v99 row_ror:2 row_mask:0xf bank_mask:0xf
	v_mov_b32_dpp v130, v112 row_ror:1 row_mask:0xf bank_mask:0xf
	v_mov_b32_dpp v127, v112 row_ror:2 row_mask:0xf bank_mask:0xf
	v_mov_b32_dpp v135, v113 row_ror:1 row_mask:0xf bank_mask:0xf
	v_mov_b32_dpp v133, v113 row_ror:2 row_mask:0xf bank_mask:0xf
	v_mov_b32_dpp v75, v102 row_ror:1 row_mask:0xf bank_mask:0xf
	v_mov_b32_dpp v0, v102 row_ror:2 row_mask:0xf bank_mask:0xf
	v_mov_b32_dpp v123, v103 row_ror:1 row_mask:0xf bank_mask:0xf
	v_mov_b32_dpp v122, v103 row_ror:2 row_mask:0xf bank_mask:0xf
	v_mov_b32_dpp v151, v82 row_ror:1 row_mask:0xf bank_mask:0xf
	v_mov_b32_dpp v150, v82 row_ror:2 row_mask:0xf bank_mask:0xf
	v_mov_b32_dpp v155, v83 row_ror:1 row_mask:0xf bank_mask:0xf
	v_mov_b32_dpp v154, v83 row_ror:2 row_mask:0xf bank_mask:0xf
	v_mov_b32_dpp v128, v80 row_ror:1 row_mask:0xf bank_mask:0xf
	v_mov_b32_dpp v126, v80 row_ror:2 row_mask:0xf bank_mask:0xf
	v_mov_b32_dpp v134, v81 row_ror:1 row_mask:0xf bank_mask:0xf
	v_mov_b32_dpp v132, v81 row_ror:2 row_mask:0xf bank_mask:0xf
	v_lshl_add_u64 v[42:43], s[96:97], 0, v[54:55]
	v_lshl_add_u64 v[44:45], s[62:63], 0, v[54:55]
	global_load_dwordx4 v[50:53], v[42:43], off
	global_load_dwordx4 v[46:49], v[44:45], off
	v_lshl_add_u64 v[42:43], s[64:65], 0, v[54:55]
	v_lshl_add_u64 v[54:55], s[66:67], 0, v[54:55]
	global_load_dwordx4 v[42:45], v[42:43], off
	s_nop 1
	global_load_dwordx4 v[54:57], v[54:55], off
	s_nop 1
	v_mov_b32_dpp v104, v88 row_ror:1 row_mask:0xf bank_mask:0xf
	v_mov_b32_dpp v108, v88 row_ror:2 row_mask:0xf bank_mask:0xf
	v_mov_b32_dpp v105, v89 row_ror:1 row_mask:0xf bank_mask:0xf
	v_mov_b32_dpp v109, v89 row_ror:2 row_mask:0xf bank_mask:0xf
	v_mov_b32_dpp v106, v86 row_ror:1 row_mask:0xf bank_mask:0xf
	v_mov_b32_dpp v110, v86 row_ror:2 row_mask:0xf bank_mask:0xf
	v_mov_b32_dpp v107, v87 row_ror:1 row_mask:0xf bank_mask:0xf
	v_mov_b32_dpp v111, v87 row_ror:2 row_mask:0xf bank_mask:0xf
	s_and_saveexec_b64 s[0:1], vcc
	s_cbranch_execz .Lcg_skip2
	s_waitcnt vmcnt(4)
	v_pk_fma_f32 v[156:157], v[60:61], v[114:115], v[72:73]
	s_nop 0
	v_pk_fma_f32 v[156:157], v[64:65], v[116:117], v[156:157]
	s_nop 0
	v_pk_fma_f32 v[92:93], v[92:93], v[68:69], v[156:157]
	v_pk_fma_f32 v[156:157], v[58:59], v[118:119], v[70:71]
	v_mul_f32_e32 v85, 0xbfb8aa3b, v93
	v_exp_f32_e32 v85, v85
	v_pk_fma_f32 v[156:157], v[62:63], v[120:121], v[156:157]
	v_mul_f32_e32 v158, 0xbfb8aa3b, v92
	v_pk_fma_f32 v[90:91], v[90:91], v[66:67], v[156:157]
	v_add_f32_e32 v85, 1.0, v85
	v_rcp_f32_e32 v159, v85
	v_mul_f32_e32 v85, 0xbfb8aa3b, v91
	v_exp_f32_e32 v85, v85
	v_mul_f32_e32 v156, 0xbfb8aa3b, v90
	v_exp_f32_e32 v158, v158
	v_exp_f32_e32 v156, v156
	v_add_f32_e32 v85, 1.0, v85
	v_rcp_f32_e32 v157, v85
	v_add_f32_e32 v158, 1.0, v158
	v_add_f32_e32 v85, 1.0, v156
	v_rcp_f32_e32 v156, v85
	v_rcp_f32_e32 v158, v158
	v_pk_mul_f32 v[90:91], v[90:91], v[156:157]
	v_pk_mul_f32 v[92:93], v[92:93], v[158:159]
	s_waitcnt vmcnt(0)
	v_pk_fma_f32 v[156:157], v[52:53], v[110:111], v[56:57]
	v_pk_fma_f32 v[158:159], v[50:51], v[108:109], v[54:55]
	v_pk_fma_f32 v[156:157], v[48:49], v[106:107], v[156:157]
	v_pk_fma_f32 v[158:159], v[46:47], v[104:105], v[158:159]
	v_pk_fma_f32 v[86:87], v[86:87], v[44:45], v[156:157]
	v_pk_fma_f32 v[88:89], v[88:89], v[42:43], v[158:159]
	v_pk_mul_f32 v[86:87], v[92:93], v[86:87]
	v_pk_mul_f32 v[88:89], v[90:91], v[88:89]
	s_nop 0
	v_cvt_pk_bf16_f32 v88, v88, v89
	v_cvt_pk_bf16_f32 v89, v86, v87
	v_mov_b64_e32 v[86:87], s[36:37]
	v_mad_i64_i32 v[86:87], s[6:7], v74, s46, v[86:87]
	v_lshl_add_u64 v[86:87], v[94:95], 1, v[86:87]
	global_store_dwordx2 v[86:87], v[88:89], off
.LBB0_127:
	s_or_b64 exec, exec, s[0:1]
	v_cmp_eq_u32_e64 s[42:43], 0, v97
	v_cndmask_b32_e32 v89, v119, v152, vcc
	v_cndmask_b32_e32 v88, v118, v136, vcc
	v_cndmask_b32_e64 v87, v153, v121, s[42:43]
	v_cndmask_b32_e64 v86, v137, v120, s[42:43]
	s_waitcnt vmcnt(4)
	v_pk_fma_f32 v[88:89], v[58:59], v[88:89], v[70:71]
	v_cndmask_b32_e32 v93, v115, v129, vcc
	v_cndmask_b32_e32 v92, v114, v124, vcc
	v_pk_fma_f32 v[86:87], v[62:63], v[86:87], v[88:89]
	v_cndmask_b32_e64 v91, v131, v117, s[42:43]
	v_cndmask_b32_e64 v90, v125, v116, s[42:43]
	v_pk_fma_f32 v[92:93], v[60:61], v[92:93], v[72:73]
	v_pk_fma_f32 v[86:87], v[100:101], v[66:67], v[86:87]
	v_pk_fma_f32 v[90:91], v[64:65], v[90:91], v[92:93]
	v_cndmask_b32_e32 v101, v152, v133, vcc
	v_cndmask_b32_e32 v100, v136, v127, vcc
	v_pk_fma_f32 v[90:91], v[98:99], v[68:69], v[90:91]
	v_cndmask_b32_e64 v99, v135, v153, s[42:43]
	v_cndmask_b32_e64 v98, v130, v137, s[42:43]
	v_pk_fma_f32 v[100:101], v[58:59], v[100:101], v[70:71]
	v_cndmask_b32_e32 v115, v129, v122, vcc
	v_pk_fma_f32 v[98:99], v[62:63], v[98:99], v[100:101]
	v_cndmask_b32_e32 v114, v124, v0, vcc
	v_pk_fma_f32 v[98:99], v[112:113], v[66:67], v[98:99]
	v_cndmask_b32_e64 v113, v123, v131, s[42:43]
	v_cndmask_b32_e64 v112, v75, v125, s[42:43]
	v_pk_fma_f32 v[114:115], v[60:61], v[114:115], v[72:73]
	v_cndmask_b32_e32 v117, v133, v154, vcc
	v_cndmask_b32_e32 v116, v127, v150, vcc
	v_pk_fma_f32 v[112:113], v[64:65], v[112:113], v[114:115]
	v_cndmask_b32_e64 v115, v155, v135, s[42:43]
	v_cndmask_b32_e64 v114, v151, v130, s[42:43]
	v_pk_fma_f32 v[58:59], v[58:59], v[116:117], v[70:71]
	v_cndmask_b32_e32 v71, v122, v132, vcc
	v_pk_fma_f32 v[58:59], v[62:63], v[114:115], v[58:59]
	v_cndmask_b32_e32 v70, v0, v126, vcc
	v_mul_f32_e32 v88, 0xbfb8aa3b, v86
	v_mul_f32_e32 v89, 0xbfb8aa3b, v87
	v_mul_f32_e32 v92, 0xbfb8aa3b, v90
	v_mul_f32_e32 v93, 0xbfb8aa3b, v91
	v_pk_fma_f32 v[58:59], v[82:83], v[66:67], v[58:59]
	v_cndmask_b32_e64 v67, v134, v123, s[42:43]
	v_cndmask_b32_e64 v66, v128, v75, s[42:43]
	v_pk_fma_f32 v[60:61], v[60:61], v[70:71], v[72:73]
	v_exp_f32_e32 v88, v88
	v_exp_f32_e32 v89, v89
	v_exp_f32_e32 v92, v92
	v_exp_f32_e32 v93, v93
	v_pk_fma_f32 v[60:61], v[64:65], v[66:67], v[60:61]
	v_mov_b32_e32 v85, v84
	v_pk_fma_f32 v[60:61], v[80:81], v[68:69], v[60:61]
	v_mov_b32_e32 v97, v96
	v_mul_f32_e32 v0, 0xbfb8aa3b, v60
	v_exp_f32_e32 v0, v0
	v_mul_f32_e32 v64, 0xbfb8aa3b, v61
	v_mov_b32_e32 v66, v84
	v_mov_b32_e32 v67, v84
	v_add_f32_e32 v88, 1.0, v88
	v_add_f32_e32 v89, 1.0, v89
	v_add_f32_e32 v92, 1.0, v92
	v_add_f32_e32 v93, 1.0, v93
	v_exp_f32_e32 v65, v64
	v_pk_mul_f32 v[40:41], v[40:41], v[66:67]
	v_pk_mul_f32 v[38:39], v[38:39], v[84:85]
	v_pk_mul_f32 v[34:35], v[34:35], v[96:97]
	s_nop 1
	v_rcp_f32_e32 v88, v88
	v_rcp_f32_e32 v89, v89
	v_rcp_f32_e32 v92, v92
	v_rcp_f32_e32 v93, v93
	v_mov_b32_e32 v66, v96
	v_mov_b32_e32 v67, v96
	s_nop 1
	v_mov_b32_dpp v85, v38 row_ror:2 row_mask:0xf bank_mask:0xf
	s_nop 1
	v_mov_b32_dpp v97, v39 row_ror:2 row_mask:0xf bank_mask:0xf
	s_nop 1
	v_mov_b32_dpp v115, v40 row_ror:2 row_mask:0xf bank_mask:0xf
	s_nop 1
	v_mov_b32_dpp v117, v41 row_ror:2 row_mask:0xf bank_mask:0xf
	v_pk_fma_f32 v[102:103], v[102:103], v[68:69], v[112:113]
	v_pk_mul_f32 v[36:37], v[36:37], v[66:67]
	v_mov_b32_dpp v84, v38 row_ror:1 row_mask:0xf bank_mask:0xf
	v_mov_b32_dpp v96, v39 row_ror:1 row_mask:0xf bank_mask:0xf
	v_mov_b32_dpp v114, v40 row_ror:1 row_mask:0xf bank_mask:0xf
	v_mov_b32_dpp v116, v41 row_ror:1 row_mask:0xf bank_mask:0xf
	v_cndmask_b32_e32 v66, v108, v85, vcc
	v_cndmask_b32_e32 v67, v109, v97, vcc
	v_cndmask_b32_e32 v68, v110, v115, vcc
	v_cndmask_b32_e32 v69, v111, v117, vcc
	v_mul_f32_e32 v100, 0xbfb8aa3b, v98
	v_mul_f32_e32 v101, 0xbfb8aa3b, v99
	v_mul_f32_e32 v112, 0xbfb8aa3b, v102
	v_mul_f32_e32 v113, 0xbfb8aa3b, v103
	v_add_f32_e32 v0, 1.0, v0
	v_cndmask_b32_e64 v70, v84, v104, s[42:43]
	v_cndmask_b32_e64 v71, v96, v105, s[42:43]
	v_cndmask_b32_e64 v72, v114, v106, s[42:43]
	v_cndmask_b32_e64 v73, v116, v107, s[42:43]
	s_waitcnt vmcnt(1)
	v_pk_fma_f32 v[68:69], v[52:53], v[68:69], v[56:57]
	v_pk_fma_f32 v[66:67], v[50:51], v[66:67], v[54:55]
	v_exp_f32_e32 v100, v100
	v_exp_f32_e32 v101, v101
	v_exp_f32_e32 v112, v112
	v_exp_f32_e32 v113, v113
	v_rcp_f32_e32 v64, v0
	v_add_f32_e32 v0, 1.0, v65
	v_pk_fma_f32 v[68:69], v[48:49], v[72:73], v[68:69]
	v_pk_fma_f32 v[66:67], v[46:47], v[70:71], v[66:67]
	v_rcp_f32_e32 v65, v0
	v_or_b32_e32 v0, 16, v74
	v_or_b32_e32 v82, 32, v74
	v_or_b32_e32 v83, 48, v74
	v_pk_mul_f32 v[74:75], v[86:87], v[88:89]
	v_pk_mul_f32 v[80:81], v[90:91], v[92:93]
	v_pk_fma_f32 v[40:41], v[40:41], v[44:45], v[68:69]
	v_pk_fma_f32 v[38:39], v[38:39], v[42:43], v[66:67]
	v_pk_mul_f32 v[40:41], v[80:81], v[40:41]
	v_pk_mul_f32 v[38:39], v[74:75], v[38:39]
	v_add_f32_e32 v100, 1.0, v100
	v_cvt_pk_bf16_f32 v38, v38, v39
	v_cvt_pk_bf16_f32 v39, v40, v41
	v_mov_b64_e32 v[40:41], s[36:37]
	v_add_f32_e32 v101, 1.0, v101
	v_add_f32_e32 v112, 1.0, v112
	v_add_f32_e32 v113, 1.0, v113
	v_mad_i64_i32 v[66:67], s[0:1], v0, s46, v[40:41]
	v_lshlrev_b64 v[68:69], 1, v[94:95]
	s_nop 1
	v_rcp_f32_e32 v100, v100
	v_rcp_f32_e32 v101, v101
	v_rcp_f32_e32 v112, v112
	v_rcp_f32_e32 v113, v113
	v_lshl_add_u64 v[66:67], v[66:67], 0, v[68:69]
	s_nop 1
	v_mov_b32_dpp v86, v34 row_ror:2 row_mask:0xf bank_mask:0xf
	s_nop 1
	v_mov_b32_dpp v88, v35 row_ror:2 row_mask:0xf bank_mask:0xf
	s_nop 1
	v_mov_b32_dpp v90, v36 row_ror:2 row_mask:0xf bank_mask:0xf
	s_nop 1
	v_mov_b32_dpp v92, v37 row_ror:2 row_mask:0xf bank_mask:0xf
	global_store_dwordx2 v[66:67], v[38:39], off
	v_mov_b32_dpp v0, v34 row_ror:1 row_mask:0xf bank_mask:0xf
	v_mov_b32_dpp v87, v35 row_ror:1 row_mask:0xf bank_mask:0xf
	v_mov_b32_dpp v89, v36 row_ror:1 row_mask:0xf bank_mask:0xf
	v_mov_b32_dpp v91, v37 row_ror:1 row_mask:0xf bank_mask:0xf
	v_cndmask_b32_e32 v38, v85, v86, vcc
	v_cndmask_b32_e32 v39, v97, v88, vcc
	v_cndmask_b32_e32 v66, v115, v90, vcc
	v_cndmask_b32_e32 v67, v117, v92, vcc
	v_cndmask_b32_e64 v70, v0, v84, s[42:43]
	v_cndmask_b32_e64 v71, v87, v96, s[42:43]
	v_cndmask_b32_e64 v72, v89, v114, s[42:43]
	v_cndmask_b32_e64 v73, v91, v116, s[42:43]
	v_pk_fma_f32 v[66:67], v[52:53], v[66:67], v[56:57]
	v_pk_fma_f32 v[38:39], v[50:51], v[38:39], v[54:55]
	v_mul_f32_e32 v62, 0xbfb8aa3b, v58
	v_mul_f32_e32 v63, 0xbfb8aa3b, v59
	v_pk_fma_f32 v[66:67], v[48:49], v[72:73], v[66:67]
	v_pk_fma_f32 v[38:39], v[46:47], v[70:71], v[38:39]
	v_exp_f32_e32 v62, v62
	v_exp_f32_e32 v63, v63
	v_pk_mul_f32 v[74:75], v[98:99], v[100:101]
	v_pk_mul_f32 v[80:81], v[102:103], v[112:113]
	v_pk_fma_f32 v[36:37], v[36:37], v[44:45], v[66:67]
	v_pk_fma_f32 v[34:35], v[34:35], v[42:43], v[38:39]
	v_pk_mul_f32 v[36:37], v[80:81], v[36:37]
	v_pk_mul_f32 v[34:35], v[74:75], v[34:35]
	v_add_f32_e32 v62, 1.0, v62
	v_cvt_pk_bf16_f32 v34, v34, v35
	v_cvt_pk_bf16_f32 v35, v36, v37
	v_mad_i64_i32 v[36:37], s[0:1], v82, s46, v[40:41]
	v_lshl_add_u64 v[36:37], v[36:37], 0, v[68:69]
	v_add_f32_e32 v63, 1.0, v63
	global_store_dwordx2 v[36:37], v[34:35], off
	s_nop 1
	v_rcp_f32_e32 v62, v62
	v_rcp_f32_e32 v63, v63
	s_nop 1
	v_mov_b32_dpp v34, v78 row_ror:2 row_mask:0xf bank_mask:0xf
	s_nop 1
	v_mov_b32_dpp v35, v79 row_ror:2 row_mask:0xf bank_mask:0xf
	s_nop 1
	v_mov_b32_dpp v36, v76 row_ror:2 row_mask:0xf bank_mask:0xf
	s_nop 1
	v_mov_b32_dpp v37, v77 row_ror:2 row_mask:0xf bank_mask:0xf
	v_mov_b32_dpp v38, v78 row_ror:1 row_mask:0xf bank_mask:0xf
	v_mov_b32_dpp v39, v79 row_ror:1 row_mask:0xf bank_mask:0xf
	v_mov_b32_dpp v66, v76 row_ror:1 row_mask:0xf bank_mask:0xf
	v_mov_b32_dpp v67, v77 row_ror:1 row_mask:0xf bank_mask:0xf
	v_cndmask_b32_e32 v34, v86, v34, vcc
	v_cndmask_b32_e32 v35, v88, v35, vcc
	v_cndmask_b32_e32 v36, v90, v36, vcc
	v_cndmask_b32_e32 v37, v92, v37, vcc
	v_cndmask_b32_e64 v38, v38, v0, s[42:43]
	v_cndmask_b32_e64 v39, v39, v87, s[42:43]
	v_cndmask_b32_e64 v66, v66, v89, s[42:43]
	v_cndmask_b32_e64 v67, v67, v91, s[42:43]
	v_pk_fma_f32 v[34:35], v[50:51], v[34:35], v[54:55]
	v_pk_fma_f32 v[36:37], v[52:53], v[36:37], v[56:57]
	v_pk_fma_f32 v[34:35], v[46:47], v[38:39], v[34:35]
	v_pk_fma_f32 v[36:37], v[48:49], v[66:67], v[36:37]
	v_pk_mul_f32 v[58:59], v[58:59], v[62:63]
	v_pk_mul_f32 v[60:61], v[60:61], v[64:65]
	v_pk_fma_f32 v[34:35], v[78:79], v[42:43], v[34:35]
	v_pk_fma_f32 v[36:37], v[76:77], v[44:45], v[36:37]
	v_pk_mul_f32 v[34:35], v[58:59], v[34:35]
	v_pk_mul_f32 v[36:37], v[60:61], v[36:37]
	v_cvt_pk_bf16_f32 v34, v34, v35
	s_nop 0
	v_cvt_pk_bf16_f32 v35, v36, v37
	v_mad_i64_i32 v[36:37], s[0:1], v83, s46, v[40:41]
	v_lshl_add_u64 v[36:37], v[36:37], 0, v[68:69]
	global_store_dwordx2 v[36:37], v[34:35], off
	s_nop 0
	v_and_b32_e32 v108, 15, v226
	v_or_b32_e32 v56, s4, v108
	v_ashrrev_i32_e32 v57, 31, v56
	v_lshl_add_u64 v[40:41], v[56:57], 3, s[38:39]
	global_load_dwordx2 v[42:43], v[40:41], off offset:1024
	global_load_dwordx2 v[38:39], v[40:41], off offset:1152
	global_load_dwordx2 v[36:37], v[40:41], off offset:1280
	s_nop 0
	global_load_dwordx2 v[40:41], v[40:41], off offset:1408
	v_ashrrev_i32_e32 v0, 1, v226
	v_and_b32_e32 v0, -8, v0
	v_add_u32_e32 v34, s21, v0
	s_waitcnt vmcnt(3)
	v_ffbh_u32_e32 v0, v43
	v_min_u32_e32 v0, 32, v0
	v_lshlrev_b64 v[42:43], v0, v[42:43]
	v_min_u32_e32 v35, 1, v42
	v_or_b32_e32 v35, v43, v35
	v_cvt_f32_u32_e32 v35, v35
	v_sub_u32_e32 v0, 32, v0
	v_ldexp_f32 v0, v35, v0
	v_mul_f32_e32 v0, 0x33800000, v0
	v_fmamk_f32 v0, v0, 0x3a800000, v210
	s_nop 0
	v_rsq_f32_e32 v0, v0
	s_nop 0
	s_nop 0
	v_ashrrev_i32_e32 v35, 31, v34
	v_pk_mul_f32 v[84:85], v[32:33], v[0:1] op_sel_hi:[1,0]
	v_pk_mul_f32 v[44:45], v[30:31], v[0:1] op_sel_hi:[1,0]
	v_pk_mul_f32 v[72:73], v[28:29], v[0:1] op_sel_hi:[1,0]
	v_pk_mul_f32 v[42:43], v[26:27], v[0:1] op_sel_hi:[1,0]
	v_lshl_add_u64 v[26:27], v[34:35], 1, s[78:79]
	v_cmp_gt_u32_e32 vcc, 2, v108
	s_and_saveexec_b64 s[0:1], vcc
	s_cbranch_execz .LBB0_129
	v_mul_u32_u24_e32 v0, 0x1600, v108
	v_lshlrev_b32_e32 v0, 1, v0
	v_cvt_pk_bf16_f32 v28, v44, v45
	v_cvt_pk_bf16_f32 v29, v84, v85
	v_lshl_add_u64 v[32:33], v[26:27], 0, v[0:1]
	v_cvt_pk_bf16_f32 v30, v42, v43
	v_cvt_pk_bf16_f32 v31, v72, v73
	global_store_dwordx2 v[32:33], v[28:29], off offset:8
	global_store_dwordx2 v[32:33], v[30:31], off offset:264

.LBB0_131:
	s_or_b64 exec, exec, s[0:1]
	v_ffbh_u32_e32 v0, v39
	v_min_u32_e32 v0, 32, v0
	v_lshlrev_b64 v[14:15], v0, v[38:39]
	v_min_u32_e32 v14, 1, v14
	v_or_b32_e32 v14, v15, v14
	v_cvt_f32_u32_e32 v14, v14
	v_sub_u32_e32 v0, 32, v0
	v_add_u32_e32 v58, s5, v34
	v_ldexp_f32 v0, v14, v0
	v_mul_f32_e32 v0, 0x33800000, v0
	v_fmamk_f32 v0, v0, 0x3a800000, v210
	s_nop 0
	v_rsq_f32_e32 v0, v0
	s_nop 0
	s_nop 0
	v_mov_b32_e32 v52, v0
	v_ffbh_u32_e32 v0, v37
	v_min_u32_e32 v0, 32, v0
	v_lshlrev_b64 v[14:15], v0, v[36:37]
	v_min_u32_e32 v14, 1, v14
	v_or_b32_e32 v14, v15, v14
	v_cvt_f32_u32_e32 v14, v14
	v_sub_u32_e32 v0, 32, v0
	v_pk_mul_f32 v[60:61], v[20:21], v[52:53] op_sel_hi:[1,0]
	v_pk_mul_f32 v[54:55], v[18:19], v[52:53] op_sel_hi:[1,0]
	v_ldexp_f32 v0, v14, v0
	v_mul_f32_e32 v0, 0x33800000, v0
	v_fmamk_f32 v0, v0, 0x3a800000, v210
	s_nop 0
	v_rsq_f32_e32 v0, v0
	s_nop 0
	s_nop 0
	v_mov_b32_e32 v62, v0
	v_pk_mul_f32 v[88:89], v[12:13], v[62:63] op_sel_hi:[1,0]
	v_pk_mul_f32 v[82:83], v[10:11], v[62:63] op_sel_hi:[1,0]
	v_ashrrev_i32_e32 v59, 31, v58
	v_lshlrev_b64 v[22:23], 2, v[58:59]
	v_lshl_add_u64 v[10:11], s[44:45], 0, v[22:23]
	v_lshl_add_u64 v[12:13], s[60:61], 0, v[22:23]
	global_load_dwordx4 v[26:29], v[10:11], off
	global_load_dwordx4 v[30:33], v[12:13], off
	v_lshl_add_u64 v[10:11], s[2:3], 0, v[22:23]
	global_load_dwordx4 v[34:37], v[10:11], off
	v_lshl_add_u64 v[10:11], s[48:49], 0, v[22:23]
	global_load_dwordx4 v[38:41], v[10:11], off
	s_nop 1
	v_cmp_lt_u32_e32 vcc, 1, v108
	v_mov_b32_dpp v66, v44 row_ror:1 row_mask:0xf bank_mask:0xf
	v_mov_b32_dpp v87, v44 row_ror:2 row_mask:0xf bank_mask:0xf
	v_mov_b32_dpp v67, v45 row_ror:1 row_mask:0xf bank_mask:0xf
	v_mov_b32_dpp v86, v45 row_ror:2 row_mask:0xf bank_mask:0xf
	v_mov_b32_dpp v80, v84 row_ror:1 row_mask:0xf bank_mask:0xf
	v_mov_b32_dpp v91, v84 row_ror:2 row_mask:0xf bank_mask:0xf
	v_mov_b32_dpp v81, v85 row_ror:1 row_mask:0xf bank_mask:0xf
	v_mov_b32_dpp v90, v85 row_ror:2 row_mask:0xf bank_mask:0xf
	v_mov_b32_dpp v0, v54 row_ror:1 row_mask:0xf bank_mask:0xf
	v_mov_b32_dpp v97, v54 row_ror:2 row_mask:0xf bank_mask:0xf
	v_mov_b32_dpp v109, v55 row_ror:1 row_mask:0xf bank_mask:0xf
	v_mov_b32_dpp v96, v55 row_ror:2 row_mask:0xf bank_mask:0xf
	v_mov_b32_dpp v110, v60 row_ror:1 row_mask:0xf bank_mask:0xf
	v_mov_b32_dpp v99, v60 row_ror:2 row_mask:0xf bank_mask:0xf
	v_mov_b32_dpp v111, v61 row_ror:1 row_mask:0xf bank_mask:0xf
	v_mov_b32_dpp v98, v61 row_ror:2 row_mask:0xf bank_mask:0xf
	v_mov_b32_dpp v112, v82 row_ror:1 row_mask:0xf bank_mask:0xf
	v_mov_b32_dpp v93, v82 row_ror:2 row_mask:0xf bank_mask:0xf
	v_mov_b32_dpp v113, v83 row_ror:1 row_mask:0xf bank_mask:0xf
	v_mov_b32_dpp v92, v83 row_ror:2 row_mask:0xf bank_mask:0xf
	v_mov_b32_dpp v114, v88 row_ror:1 row_mask:0xf bank_mask:0xf
	v_mov_b32_dpp v95, v88 row_ror:2 row_mask:0xf bank_mask:0xf
	v_mov_b32_dpp v115, v89 row_ror:1 row_mask:0xf bank_mask:0xf
	v_mov_b32_dpp v94, v89 row_ror:2 row_mask:0xf bank_mask:0xf
	v_mov_b32_dpp v57, v64 row_ror:1 row_mask:0xf bank_mask:0xf
	v_mov_b32_dpp v101, v64 row_ror:2 row_mask:0xf bank_mask:0xf
	v_mov_b32_dpp v116, v65 row_ror:1 row_mask:0xf bank_mask:0xf
	v_mov_b32_dpp v100, v65 row_ror:2 row_mask:0xf bank_mask:0xf
	v_mov_b32_dpp v117, v68 row_ror:1 row_mask:0xf bank_mask:0xf
	v_mov_b32_dpp v103, v68 row_ror:2 row_mask:0xf bank_mask:0xf
	v_mov_b32_dpp v118, v69 row_ror:1 row_mask:0xf bank_mask:0xf
	v_mov_b32_dpp v102, v69 row_ror:2 row_mask:0xf bank_mask:0xf
	v_cmp_gt_u32_e64 s[42:43], 2, v108
	v_lshl_add_u64 v[10:11], s[96:97], 0, v[22:23]
	v_lshl_add_u64 v[12:13], s[62:63], 0, v[22:23]
	global_load_dwordx4 v[18:21], v[10:11], off
	global_load_dwordx4 v[14:17], v[12:13], off
	v_lshl_add_u64 v[10:11], s[64:65], 0, v[22:23]
	v_lshl_add_u64 v[22:23], s[66:67], 0, v[22:23]
	global_load_dwordx4 v[10:13], v[10:11], off
	s_nop 1
	global_load_dwordx4 v[22:25], v[22:23], off
	s_nop 1
	v_mov_b32_dpp v70, v42 row_ror:1 row_mask:0xf bank_mask:0xf
	v_mov_b32_dpp v76, v42 row_ror:2 row_mask:0xf bank_mask:0xf
	v_mov_b32_dpp v71, v43 row_ror:1 row_mask:0xf bank_mask:0xf
	v_mov_b32_dpp v77, v43 row_ror:2 row_mask:0xf bank_mask:0xf
	v_mov_b32_dpp v74, v72 row_ror:1 row_mask:0xf bank_mask:0xf
	v_mov_b32_dpp v78, v72 row_ror:2 row_mask:0xf bank_mask:0xf
	v_mov_b32_dpp v75, v73 row_ror:1 row_mask:0xf bank_mask:0xf
	v_mov_b32_dpp v79, v73 row_ror:2 row_mask:0xf bank_mask:0xf
	s_and_saveexec_b64 s[0:1], s[42:43]
	s_xor_b64 s[0:1], exec, s[0:1]
	s_or_saveexec_b64 s[0:1], s[0:1]
	v_mov_b64_e32 v[106:107], v[98:99]
	v_mov_b64_e32 v[104:105], v[96:97]
	s_xor_b64 exec, exec, s[0:1]
	s_cbranch_execz .Lcg_skip3
	s_waitcnt vmcnt(4)
	v_pk_fma_f32 v[46:47], v[28:29], v[90:91], v[40:41] op_sel:[0,1,0] op_sel_hi:[1,0,1]
	v_mov_b64_e32 v[106:107], v[94:95]
	v_pk_fma_f32 v[46:47], v[32:33], v[80:81], v[46:47]
	v_mov_b64_e32 v[104:105], v[92:93]
	v_pk_fma_f32 v[46:47], v[84:85], v[36:37], v[46:47]
	v_pk_fma_f32 v[84:85], v[26:27], v[86:87], v[38:39] op_sel:[0,1,0] op_sel_hi:[1,0,1]
	v_mul_f32_e32 v53, 0xbfb8aa3b, v47
	v_exp_f32_e32 v53, v53
	v_pk_fma_f32 v[84:85], v[30:31], v[66:67], v[84:85]
	v_mul_f32_e32 v63, 0xbfb8aa3b, v46
	v_pk_fma_f32 v[44:45], v[44:45], v[34:35], v[84:85]
	v_add_f32_e32 v53, 1.0, v53
	v_exp_f32_e32 v63, v63
	v_rcp_f32_e32 v87, v53
	v_mul_f32_e32 v53, 0xbfb8aa3b, v45
	v_exp_f32_e32 v53, v53
	v_mul_f32_e32 v84, 0xbfb8aa3b, v44
	v_exp_f32_e32 v84, v84
	v_add_f32_e32 v63, 1.0, v63
	v_add_f32_e32 v53, 1.0, v53
	v_rcp_f32_e32 v86, v63
	v_rcp_f32_e32 v85, v53
	v_add_f32_e32 v53, 1.0, v84
	v_rcp_f32_e32 v84, v53
	v_pk_mul_f32 v[46:47], v[46:47], v[86:87]
	s_waitcnt vmcnt(0)
	v_pk_fma_f32 v[86:87], v[18:19], v[76:77], v[22:23]
	v_add_u32_e32 v53, 0x80, v56
	v_pk_fma_f32 v[86:87], v[14:15], v[70:71], v[86:87]
	v_pk_mul_f32 v[44:45], v[44:45], v[84:85]
	v_pk_fma_f32 v[42:43], v[42:43], v[10:11], v[86:87]
	v_pk_fma_f32 v[84:85], v[20:21], v[78:79], v[24:25]
	v_pk_mul_f32 v[42:43], v[44:45], v[42:43]
	v_mov_b64_e32 v[44:45], s[36:37]
	v_pk_fma_f32 v[84:85], v[16:17], v[74:75], v[84:85]
	v_mad_i64_i32 v[44:45], s[4:5], v53, s46, v[44:45]
	v_pk_fma_f32 v[72:73], v[72:73], v[12:13], v[84:85]
	v_lshl_add_u64 v[44:45], v[58:59], 1, v[44:45]
	v_mov_b64_e32 v[90:91], v[98:99]
	v_mov_b64_e32 v[86:87], v[96:97]
	v_mov_b64_e32 v[94:95], v[102:103]
	v_mov_b64_e32 v[92:93], v[100:101]
	v_pk_mul_f32 v[46:47], v[46:47], v[72:73]
	v_cvt_pk_bf16_f32 v42, v42, v43
	s_nop 0
	v_cvt_pk_bf16_f32 v43, v46, v47
	global_store_dwordx2 v[44:45], v[42:43], off
.LBB0_135:
	s_or_b64 exec, exec, s[0:1]
	v_cmp_eq_u32_e64 s[42:43], 0, v108
	v_add_u32_e32 v96, 0x90, v56
	v_add_u32_e32 v97, 0xa0, v56
	v_add_u32_e32 v98, 0xb0, v56
	v_cndmask_b32_e64 v43, v118, v115, s[42:43]
	v_cndmask_b32_e64 v42, v117, v114, s[42:43]
	s_waitcnt vmcnt(4)
	v_pk_fma_f32 v[44:45], v[28:29], v[94:95], v[40:41] op_sel:[0,1,0] op_sel_hi:[1,0,1]
	v_cndmask_b32_e64 v47, v116, v113, s[42:43]
	v_cndmask_b32_e64 v46, v57, v112, s[42:43]
	v_pk_fma_f32 v[56:57], v[26:27], v[92:93], v[38:39] op_sel:[0,1,0] op_sel_hi:[1,0,1]
	v_pk_fma_f32 v[42:43], v[32:33], v[42:43], v[44:45]
	v_pk_fma_f32 v[46:47], v[30:31], v[46:47], v[56:57]
	v_pk_fma_f32 v[42:43], v[68:69], v[36:37], v[42:43]
	v_pk_fma_f32 v[46:47], v[64:65], v[34:35], v[46:47]
	v_cndmask_b32_e64 v65, v115, v111, s[42:43]
	v_cndmask_b32_e64 v64, v114, v110, s[42:43]
	v_pk_fma_f32 v[68:69], v[28:29], v[106:107], v[40:41] op_sel:[0,1,0] op_sel_hi:[1,0,1]
	v_cndmask_b32_e64 v81, v111, v81, s[42:43]
	v_cndmask_b32_e64 v80, v110, v80, s[42:43]
	v_pk_fma_f32 v[28:29], v[28:29], v[90:91], v[40:41] op_sel:[0,1,0] op_sel_hi:[1,0,1]
	v_pk_fma_f32 v[64:65], v[32:33], v[64:65], v[68:69]
	v_pk_fma_f32 v[28:29], v[32:33], v[80:81], v[28:29]
	v_pk_fma_f32 v[64:65], v[88:89], v[36:37], v[64:65]
	v_pk_fma_f32 v[84:85], v[26:27], v[104:105], v[38:39] op_sel:[0,1,0] op_sel_hi:[1,0,1]
	v_pk_fma_f32 v[28:29], v[60:61], v[36:37], v[28:29]
	v_cndmask_b32_e64 v37, v109, v67, s[42:43]
	v_cndmask_b32_e64 v36, v0, v66, s[42:43]
	v_pk_fma_f32 v[26:27], v[26:27], v[86:87], v[38:39] op_sel:[0,1,0] op_sel_hi:[1,0,1]
	v_cndmask_b32_e64 v72, v112, v0, s[42:43]
	v_pk_fma_f32 v[26:27], v[30:31], v[36:37], v[26:27]
	v_mul_f32_e32 v32, 0xbfb8aa3b, v29
	v_pk_fma_f32 v[26:27], v[54:55], v[34:35], v[26:27]
	v_exp_f32_e32 v32, v32
	v_mul_f32_e32 v0, 0xbfb8aa3b, v27
	v_exp_f32_e32 v0, v0
	v_cndmask_b32_e64 v73, v113, v109, s[42:43]
	v_add_f32_e32 v32, 1.0, v32
	v_pk_fma_f32 v[72:73], v[30:31], v[72:73], v[84:85]
	v_add_f32_e32 v0, 1.0, v0
	v_rcp_f32_e32 v33, v32
	v_mul_f32_e32 v32, 0xbfb8aa3b, v28
	v_rcp_f32_e32 v31, v0
	v_mul_f32_e32 v0, 0xbfb8aa3b, v26
	v_exp_f32_e32 v32, v32
	v_exp_f32_e32 v0, v0
	v_pk_fma_f32 v[72:73], v[82:83], v[34:35], v[72:73]
	v_mul_f32_e32 v68, 0xbfb8aa3b, v65
	v_mul_f32_e32 v82, 0xbfb8aa3b, v73
	v_exp_f32_e32 v68, v68
	v_exp_f32_e32 v82, v82
	v_add_f32_e32 v32, 1.0, v32
	v_add_f32_e32 v0, 1.0, v0
	v_mov_b32_e32 v34, v62
	v_mov_b32_e32 v35, v62
	v_mov_b32_e32 v53, v52
	v_mov_b32_e32 v63, v62
	v_rcp_f32_e32 v32, v32
	v_rcp_f32_e32 v30, v0
	v_pk_mul_f32 v[4:5], v[4:5], v[34:35]
	v_mov_b32_e32 v34, v52
	v_mov_b32_e32 v35, v52
	v_pk_mul_f32 v[2:3], v[2:3], v[62:63]
	v_pk_mul_f32 v[8:9], v[8:9], v[34:35]
	v_pk_mul_f32 v[6:7], v[6:7], v[52:53]
	s_nop 1
	v_mov_b32_dpp v52, v6 row_ror:2 row_mask:0xf bank_mask:0xf
	s_nop 1
	v_mov_b32_dpp v54, v7 row_ror:2 row_mask:0xf bank_mask:0xf
	s_nop 1
	v_mov_b32_dpp v60, v8 row_ror:2 row_mask:0xf bank_mask:0xf
	s_nop 1
	v_mov_b32_dpp v62, v9 row_ror:2 row_mask:0xf bank_mask:0xf
	v_add_f32_e32 v68, 1.0, v68
	v_add_f32_e32 v82, 1.0, v82
	v_mov_b32_dpp v0, v6 row_ror:1 row_mask:0xf bank_mask:0xf
	v_mov_b32_dpp v53, v7 row_ror:1 row_mask:0xf bank_mask:0xf
	v_mov_b32_dpp v55, v8 row_ror:1 row_mask:0xf bank_mask:0xf
	v_mov_b32_dpp v61, v9 row_ror:1 row_mask:0xf bank_mask:0xf
	v_cndmask_b32_e32 v34, v76, v52, vcc
	v_cndmask_b32_e32 v35, v77, v54, vcc
	v_cndmask_b32_e32 v36, v78, v60, vcc
	v_cndmask_b32_e32 v37, v79, v62, vcc
	v_rcp_f32_e32 v69, v68
	v_mul_f32_e32 v68, 0xbfb8aa3b, v64
	v_rcp_f32_e32 v83, v82
	v_mul_f32_e32 v82, 0xbfb8aa3b, v72
	v_cndmask_b32_e64 v38, v0, v70, s[42:43]
	v_cndmask_b32_e64 v39, v53, v71, s[42:43]
	v_cndmask_b32_e64 v40, v55, v74, s[42:43]
	v_cndmask_b32_e64 v41, v61, v75, s[42:43]
	v_pk_mul_f32 v[26:27], v[26:27], v[30:31]
	v_pk_mul_f32 v[28:29], v[28:29], v[32:33]
	s_waitcnt vmcnt(1)
	v_pk_fma_f32 v[30:31], v[20:21], v[36:37], v[24:25]
	v_pk_fma_f32 v[32:33], v[18:19], v[34:35], v[22:23]
	v_exp_f32_e32 v68, v68
	v_exp_f32_e32 v82, v82
	v_pk_fma_f32 v[30:31], v[16:17], v[40:41], v[30:31]
	v_pk_fma_f32 v[32:33], v[14:15], v[38:39], v[32:33]
	v_pk_fma_f32 v[8:9], v[8:9], v[12:13], v[30:31]
	v_pk_fma_f32 v[6:7], v[6:7], v[10:11], v[32:33]
	v_mul_f32_e32 v44, 0xbfb8aa3b, v43
	v_mul_f32_e32 v56, 0xbfb8aa3b, v47
	v_pk_mul_f32 v[8:9], v[28:29], v[8:9]
	v_pk_mul_f32 v[6:7], v[26:27], v[6:7]
	v_exp_f32_e32 v44, v44
	v_exp_f32_e32 v56, v56
	v_cvt_pk_bf16_f32 v6, v6, v7
	v_cvt_pk_bf16_f32 v7, v8, v9
	v_mov_b64_e32 v[8:9], s[36:37]
	v_add_f32_e32 v68, 1.0, v68
	v_add_f32_e32 v82, 1.0, v82
	v_mad_i64_i32 v[26:27], s[0:1], v96, s46, v[8:9]
	v_lshlrev_b64 v[28:29], 1, v[58:59]
	s_nop 1
	v_rcp_f32_e32 v68, v68
	v_rcp_f32_e32 v82, v82
	v_lshl_add_u64 v[26:27], v[26:27], 0, v[28:29]
	s_nop 1
	v_mov_b32_dpp v39, v2 row_ror:2 row_mask:0xf bank_mask:0xf
	s_nop 1
	v_mov_b32_dpp v41, v3 row_ror:2 row_mask:0xf bank_mask:0xf
	s_nop 1
	v_mov_b32_dpp v59, v4 row_ror:2 row_mask:0xf bank_mask:0xf
	s_nop 1
	v_mov_b32_dpp v66, v5 row_ror:2 row_mask:0xf bank_mask:0xf
	global_store_dwordx2 v[26:27], v[6:7], off
	v_mov_b32_dpp v38, v2 row_ror:1 row_mask:0xf bank_mask:0xf
	v_mov_b32_dpp v40, v3 row_ror:1 row_mask:0xf bank_mask:0xf
	v_mov_b32_dpp v58, v4 row_ror:1 row_mask:0xf bank_mask:0xf
	v_mov_b32_dpp v63, v5 row_ror:1 row_mask:0xf bank_mask:0xf
	v_cndmask_b32_e32 v6, v52, v39, vcc
	v_cndmask_b32_e32 v7, v54, v41, vcc
	v_cndmask_b32_e32 v26, v60, v59, vcc
	v_cndmask_b32_e32 v27, v62, v66, vcc
	v_add_f32_e32 v44, 1.0, v44
	v_add_f32_e32 v56, 1.0, v56
	v_cndmask_b32_e64 v30, v38, v0, s[42:43]
	v_cndmask_b32_e64 v31, v40, v53, s[42:43]
	v_cndmask_b32_e64 v32, v58, v55, s[42:43]
	v_cndmask_b32_e64 v33, v63, v61, s[42:43]
	v_pk_fma_f32 v[26:27], v[20:21], v[26:27], v[24:25]
	v_pk_fma_f32 v[6:7], v[18:19], v[6:7], v[22:23]
	v_rcp_f32_e32 v45, v44
	v_mul_f32_e32 v44, 0xbfb8aa3b, v42
	v_rcp_f32_e32 v57, v56
	v_mul_f32_e32 v56, 0xbfb8aa3b, v46
	v_pk_fma_f32 v[26:27], v[16:17], v[32:33], v[26:27]
	v_pk_fma_f32 v[6:7], v[14:15], v[30:31], v[6:7]
	v_exp_f32_e32 v44, v44
	v_exp_f32_e32 v56, v56
	v_pk_mul_f32 v[34:35], v[72:73], v[82:83]
	v_pk_mul_f32 v[36:37], v[64:65], v[68:69]
	v_pk_fma_f32 v[4:5], v[4:5], v[12:13], v[26:27]
	v_pk_fma_f32 v[2:3], v[2:3], v[10:11], v[6:7]
	v_pk_mul_f32 v[4:5], v[36:37], v[4:5]
	v_pk_mul_f32 v[2:3], v[34:35], v[2:3]
	v_add_f32_e32 v44, 1.0, v44
	v_cvt_pk_bf16_f32 v2, v2, v3
	v_cvt_pk_bf16_f32 v3, v4, v5
	v_mad_i64_i32 v[4:5], s[0:1], v97, s46, v[8:9]
	v_lshl_add_u64 v[4:5], v[4:5], 0, v[28:29]
	v_add_f32_e32 v56, 1.0, v56
	global_store_dwordx2 v[4:5], v[2:3], off
	s_nop 1
	v_rcp_f32_e32 v44, v44
	v_rcp_f32_e32 v56, v56
	s_nop 1
	v_mov_b32_dpp v2, v50 row_ror:2 row_mask:0xf bank_mask:0xf
	s_nop 1
	v_mov_b32_dpp v3, v51 row_ror:2 row_mask:0xf bank_mask:0xf
	s_nop 1
	v_mov_b32_dpp v4, v48 row_ror:2 row_mask:0xf bank_mask:0xf
	s_nop 1
	v_mov_b32_dpp v5, v49 row_ror:2 row_mask:0xf bank_mask:0xf
	v_mov_b32_dpp v0, v50 row_ror:1 row_mask:0xf bank_mask:0xf
	v_mov_b32_dpp v7, v51 row_ror:1 row_mask:0xf bank_mask:0xf
	v_mov_b32_dpp v26, v48 row_ror:1 row_mask:0xf bank_mask:0xf
	v_mov_b32_dpp v27, v49 row_ror:1 row_mask:0xf bank_mask:0xf
	v_cndmask_b32_e32 v2, v39, v2, vcc
	v_cndmask_b32_e32 v3, v41, v3, vcc
	v_cndmask_b32_e32 v4, v59, v4, vcc
	v_cndmask_b32_e32 v5, v66, v5, vcc
	v_cndmask_b32_e64 v6, v0, v38, s[42:43]
	v_cndmask_b32_e64 v7, v7, v40, s[42:43]
	v_cndmask_b32_e64 v26, v26, v58, s[42:43]
	v_cndmask_b32_e64 v27, v27, v63, s[42:43]
	v_pk_fma_f32 v[2:3], v[18:19], v[2:3], v[22:23]
	v_pk_fma_f32 v[4:5], v[20:21], v[4:5], v[24:25]
	v_pk_fma_f32 v[2:3], v[14:15], v[6:7], v[2:3]
	v_pk_fma_f32 v[4:5], v[16:17], v[26:27], v[4:5]
	v_pk_mul_f32 v[30:31], v[46:47], v[56:57]
	v_pk_mul_f32 v[32:33], v[42:43], v[44:45]
	v_pk_fma_f32 v[2:3], v[50:51], v[10:11], v[2:3]
	v_pk_fma_f32 v[4:5], v[48:49], v[12:13], v[4:5]
	v_pk_mul_f32 v[2:3], v[30:31], v[2:3]
	v_pk_mul_f32 v[4:5], v[32:33], v[4:5]
	v_cvt_pk_bf16_f32 v2, v2, v3
	s_nop 0
	v_cvt_pk_bf16_f32 v3, v4, v5
	v_mad_i64_i32 v[4:5], s[0:1], v98, s46, v[8:9]
	v_lshl_add_u64 v[4:5], v[4:5], 0, v[28:29]
	global_store_dwordx2 v[4:5], v[2:3], off
	s_andn2_b64 vcc, exec, s[40:41]
	s_mov_b64 s[0:1], -1
	s_cbranch_vccnz .LBB0_102
	s_andn2_b64 vcc, exec, s[30:31]
	s_cbranch_vccnz .LBB0_101
	s_barrier
	s_branch .LBB0_101
